# fsub + new grid barriers + nt y stores + step-1 a_log load hoist + GEMM3 rowss loads hoisted + attention gate loads hoisted
# speedup vs baseline: 1.0169x; 1.0169x over previous
; __device__ __forceinline__ void dn_prep(const Params& p, LAS unsigned char* lds) {
;     ...
;         if (wid == 0) {
;             const bool valid = lane < ntok;
;             float be = 0.f, gl = 0.f;
;             if (valid) {
;                 const float bl = BA[(size_t)(row0 + lane) * 8 + h], al = BA[(size_t)(row0 + lane) * 8 + 4 + h] + p.in[14][h];
;                 be = __builtin_amdgcn_rcpf(1.0f + __expf(-bl));
;                 const float sp = al > 20.f ? al : log1pf(__expf(al));
;                 gl = -__expf(p.in[13][h]) * sp;
;             }
.LBB0_200:
	v_cmp_gt_u32_e32 vcc, s6, v152
	v_mov_b32_e32 v0, 0
	v_mov_b32_e32 v1, 0
	s_and_saveexec_b64 s[26:27], vcc
	s_cbranch_execz .LBB0_204
	v_add_u32_e32 v0, s90, v184
	v_ashrrev_i32_e32 v1, 31, v0
	v_readlane_b32 s0, v248, 8
	v_lshlrev_b64 v[0:1], 5, v[0:1]
	v_readlane_b32 s1, v248, 9
	s_lshl_b32 s40, s17, 2
	s_nop 0
	v_lshl_add_u64 v[0:1], s[0:1], 0, v[0:1]
	v_lshl_add_u64 v[2:3], v[0:1], 0, s[40:41]
	global_load_dword v0, v[2:3], off
	global_load_dword v1, v[2:3], off offset:16
	v_mov_b32_e32 v2, s40
	global_load_dword v2, v2, s[80:81]
	v_mov_b32_e32 v247, s40
	global_load_dword v247, v247, s[78:79]
	s_mov_b32 s0, 0x41a00000
	s_waitcnt vmcnt(0)
	v_add_f32_e32 v1, v1, v2
	v_cmp_nlt_f32_e32 vcc, s0, v1
	s_and_saveexec_b64 s[28:29], vcc
	s_cbranch_execz .LBB0_203
	v_mul_f32_e32 v1, 0x3fb8aa3b, v1
	v_exp_f32_e32 v1, v1
	s_mov_b32 s0, 0x3f2aaaab
	v_add_f32_e32 v4, 1.0, v1
	v_frexp_mant_f32_e32 v6, v4
	v_cvt_f64_f32_e32 v[2:3], v4
	v_frexp_exp_i32_f64_e32 v2, v[2:3]
	v_cmp_gt_f32_e32 vcc, s0, v6
	v_add_f32_e32 v5, -1.0, v4
	v_sub_f32_e32 v7, v5, v4
	v_subbrev_co_u32_e32 v10, vcc, 0, v2, vcc
	v_sub_u32_e32 v2, 0, v10
	v_sub_f32_e32 v5, v1, v5
	v_add_f32_e32 v7, 1.0, v7
	v_ldexp_f32 v3, v4, v2
	v_add_f32_e32 v5, v5, v7
	v_add_f32_e32 v4, -1.0, v3
	v_add_f32_e32 v6, 1.0, v3
	v_ldexp_f32 v2, v5, v2
	v_add_f32_e32 v5, 1.0, v4
	v_add_f32_e32 v7, -1.0, v6
	v_sub_f32_e32 v5, v3, v5
	v_sub_f32_e32 v3, v3, v7
	v_add_f32_e32 v5, v2, v5
	v_add_f32_e32 v2, v2, v3
	v_add_f32_e32 v11, v6, v2
	v_rcp_f32_e32 v13, v11
	v_sub_f32_e32 v3, v11, v6
	v_sub_f32_e32 v12, v2, v3
	v_add_f32_e32 v3, v4, v5
	v_mul_f32_e32 v15, v3, v13
	v_sub_f32_e32 v2, v3, v4
	v_mul_f32_e32 v4, v11, v15
	v_fma_f32 v6, v15, v11, -v4
	v_fmac_f32_e32 v6, v15, v12
	v_sub_f32_e32 v14, v5, v2
	v_add_f32_e32 v2, v4, v6
	v_sub_f32_e32 v5, v3, v2
	v_pk_add_f32 v[8:9], v[2:3], v[4:5] neg_lo:[0,1] neg_hi:[0,1]
	v_mov_b32_e32 v7, v2
	v_pk_add_f32 v[2:3], v[8:9], v[6:7] neg_lo:[0,1] neg_hi:[0,1]
	s_mov_b32 s0, 0x3f317218
	v_add_f32_e32 v3, v14, v3
	v_add_f32_e32 v2, v2, v3
	v_add_f32_e32 v3, v5, v2
	v_mul_f32_e32 v14, v13, v3
	v_mul_f32_e32 v4, v11, v14
	v_fma_f32 v6, v14, v11, -v4
	v_fmac_f32_e32 v6, v14, v12
	v_sub_f32_e32 v5, v5, v3
	v_add_f32_e32 v11, v2, v5
	v_add_f32_e32 v2, v4, v6
	v_sub_f32_e32 v5, v3, v2
	v_pk_add_f32 v[8:9], v[2:3], v[4:5] neg_lo:[0,1] neg_hi:[0,1]
	v_mov_b32_e32 v7, v2
	v_pk_add_f32 v[2:3], v[8:9], v[6:7] neg_lo:[0,1] neg_hi:[0,1]
	s_nop 0
	v_add_f32_e32 v3, v11, v3
	v_add_f32_e32 v2, v2, v3
	v_add_f32_e32 v3, v15, v14
	v_add_f32_e32 v2, v5, v2
	v_sub_f32_e32 v4, v3, v15
	v_mul_f32_e32 v2, v13, v2
	v_sub_f32_e32 v4, v14, v4
	v_add_f32_e32 v4, v4, v2
	v_add_f32_e32 v6, v3, v4
	v_mul_f32_e32 v7, v6, v6
	v_fmamk_f32 v2, v7, 0x3e9b6dac, v225
	v_fmaak_f32 v141, v7, v2, 0x3f2aaada
	v_cvt_f32_i32_e32 v2, v10
	v_sub_f32_e32 v3, v6, v3
	v_sub_f32_e32 v3, v4, v3
	v_ldexp_f32 v8, v3, 1
	v_mul_f32_e32 v3, v6, v7
	v_ldexp_f32 v5, v6, 1
	v_pk_mul_f32 v[6:7], v[2:3], v[140:141]
	s_nop 0
	v_fma_f32 v4, v2, s0, -v6
	v_fmac_f32_e32 v4, 0xb102e308, v2
	v_pk_add_f32 v[2:3], v[6:7], v[4:5]
	s_mov_b32 s0, 0x7f800000
	v_sub_f32_e32 v5, v3, v5
	v_sub_f32_e32 v5, v7, v5
	v_add_f32_e32 v9, v8, v5
	v_mov_b32_e32 v8, v6
	v_pk_add_f32 v[6:7], v[2:3], v[6:7] neg_lo:[0,1] neg_hi:[0,1]
	v_pk_add_f32 v[10:11], v[2:3], v[8:9]
	v_mov_b32_e32 v5, v2
	v_mov_b32_e32 v7, v11
	v_pk_add_f32 v[12:13], v[4:5], v[6:7] neg_lo:[0,1] neg_hi:[0,1]
	v_pk_add_f32 v[4:5], v[4:5], v[6:7]
	v_mov_b32_e32 v8, v9
	v_pk_add_f32 v[6:7], v[4:5], v[2:3] op_sel:[1,0] op_sel_hi:[0,1] neg_lo:[0,1] neg_hi:[0,1]
	v_pk_add_f32 v[14:15], v[10:11], v[6:7] op_sel_hi:[1,0] neg_lo:[0,1] neg_hi:[0,1]
	v_mov_b32_e32 v10, v11
	v_mov_b32_e32 v11, v5
	v_pk_mov_b32 v[6:7], v[2:3], v[6:7] op_sel:[1,0]
	v_mov_b32_e32 v9, v2
	v_pk_add_f32 v[6:7], v[10:11], v[6:7] neg_lo:[0,1] neg_hi:[0,1]
	v_mov_b32_e32 v14, v12
	v_pk_add_f32 v[2:3], v[8:9], v[6:7] neg_lo:[0,1] neg_hi:[0,1]
	v_mov_b32_e32 v13, v5
	v_pk_add_f32 v[6:7], v[14:15], v[2:3]
	v_cmp_neq_f32_e32 vcc, s0, v1
	v_pk_add_f32 v[8:9], v[6:7], v[6:7] op_sel:[0,1] op_sel_hi:[1,0]
	s_mov_b32 s0, 0x33800000
	v_pk_add_f32 v[4:5], v[4:5], v[8:9] op_sel:[1,0] op_sel_hi:[0,1]
	v_mov_b32_e32 v7, v4
	v_pk_add_f32 v[10:11], v[6:7], v[12:13] neg_lo:[0,1] neg_hi:[0,1]
	v_mov_b32_e32 v3, v8
	v_sub_f32_e32 v5, v6, v10
	v_pk_add_f32 v[2:3], v[2:3], v[10:11] neg_lo:[0,1] neg_hi:[0,1]
	v_sub_f32_e32 v5, v12, v5
	v_add_f32_e32 v2, v2, v5
	v_add_f32_e32 v2, v2, v3
	v_add_f32_e32 v2, v4, v2
	v_cndmask_b32_e32 v2, v227, v2, vcc
	v_cmp_ngt_f32_e32 vcc, -1.0, v1
	s_nop 1
	v_cndmask_b32_e32 v2, v228, v2, vcc
	v_cmp_neq_f32_e32 vcc, -1.0, v1
	s_nop 1
	v_cndmask_b32_e32 v2, v229, v2, vcc
	v_cmp_lt_f32_e64 vcc, |v1|, s0
	s_nop 1
	v_cndmask_b32_e32 v1, v2, v1, vcc
.LBB0_203:
	s_or_b64 exec, exec, s[28:29]
	v_mul_f32_e32 v0, 0xbfb8aa3b, v0
	v_exp_f32_e32 v0, v0
	v_mul_f32_e32 v2, 0x3fb8aa3b, v247
	v_add_f32_e32 v0, 1.0, v0
	v_exp_f32_e32 v2, v2
	v_rcp_f32_e32 v0, v0
	v_mul_f32_e64 v1, v1, -v2

; #define LAS __attribute__((address_space(3)))
; __device__ __forceinline__ unsigned cvt_pk_bf16(float lo, float hi) { const f32v2_t v = {lo, hi}; const bf16v2_t r = __builtin_convertvector(v, bf16v2_t); return __builtin_bit_cast(unsigned, r); }
; __device__ __forceinline__ float bf2f(short b) { return __uint_as_float(((unsigned)(unsigned short)b) << 16); }
; __device__ __forceinline__ float silu_f(float x) { return x * __builtin_amdgcn_rcpf(1.0f + __expf(-x)); }
; __device__ __forceinline__ void attn_items(const Params& p, LAS unsigned char* lds, int ai0, int aistride) {
;     ...
;                 float l = 0.f;
; #pragma unroll
;                 for (int kt = 0; kt < 12; ++kt)
; #pragma unroll
;                     for (int jj = 0; jj < 4; ++jj) { const float pv = __expf(s[kt][jj] - mx); s[kt][jj] = pv; l += pv; }
;                 l += __shfl_xor(l, 16); l += __shfl_xor(l, 32);
;                 l += __expf(sink - mx);
;                 const float inv = __builtin_amdgcn_rcpf(l);
;                 f32x4 o[4];
; #pragma unroll
;                 for (int dt = 0; dt < 4; ++dt) o[dt] = (f32x4){0.f, 0.f, 0.f, 0.f};
; #pragma unroll
;                 for (int u = 0; u < 6; ++u) {
;                     if (2 * u < nkt) {
;                         const bf16x8 Pf = pack8(s[2 * u], s[2 * u + 1]);
; #pragma unroll
;                         for (int dt = 0; dt < 4; ++dt) {
;                             const u32x2 lo = *(const LAS u32x2*)(Vt_s + (16 * dt + fr) * 200 + 32 * u + 4 * fq), hi = *(const LAS u32x2*)(Vt_s + (16 * dt + fr) * 200 + 32 * u + 16 + 4 * fq);
;                             o[dt] = mfma16(cat8(lo, hi), Pf, o[dt]);
;                         }
;                     }
;                 }
; #pragma unroll
;                 for (int dt = 0; dt < 4; ++dt) {
;                     const int d = 16 * dt + 4 * fq;
;                     const bf16x4 ag = *(const bf16x4*)(Z + qrow * NZ + ZC_AG + hh * 64 + d);
;                     u32x2 w; w.x = cvt_pk_bf16(o[dt][0] * inv * silu_f(bf2f(ag[0])), o[dt][1] * inv * silu_f(bf2f(ag[1])));
;                     w.y = cvt_pk_bf16(o[dt][2] * inv * silu_f(bf2f(ag[2])), o[dt][3] * inv * silu_f(bf2f(ag[3])));
;                     *(u32x2*)(CAT + qrow * DM + hh * 64 + d) = w;
;                 }
.LBB0_544:
	v_ashrrev_i32_e32 v27, 31, v26
	v_lshlrev_b32_e32 v16, 6, v28
	v_lshlrev_b64 v[26:27], 11, v[26:27]
	v_lshl_add_u64 v[26:27], s[16:17], 0, v[26:27]
	v_lshlrev_b32_e32 v16, 1, v16
	v_lshl_add_u64 v[26:27], v[26:27], 0, v[16:17]
	v_lshlrev_b32_e32 v16, 1, v18
	v_sub_f32_e32 v23, v23, v29
	v_mul_f32_e32 v23, 0x3fb8aa3b, v23
	v_exp_f32_e32 v23, v23
	s_waitcnt lgkmcnt(0)
	v_add_f32_e32 v28, v30, v31
	v_lshl_add_u64 v[26:27], v[26:27], 0, v[16:17]
	v_add_f32_e32 v23, v23, v28
	v_rcp_f32_e32 v28, v23
	v_and_b32_e32 v31, 0xffff0000, v232
	v_lshlrev_b32_e32 v30, 16, v232
	v_and_b32_e32 v39, 0xffff0000, v233
	v_lshlrev_b32_e32 v38, 16, v233
	v_pk_mul_f32 v[8:9], v[28:29], v[8:9] op_sel_hi:[0,1]
	v_pk_mul_f32 v[10:11], v[28:29], v[10:11] op_sel_hi:[0,1]
	v_pk_mul_f32 v[12:13], v[28:29], v[12:13] op_sel_hi:[0,1]
	v_pk_mul_f32 v[14:15], v[28:29], v[14:15] op_sel_hi:[0,1]
	v_pk_mul_f32 v[4:5], v[28:29], v[4:5] op_sel_hi:[0,1]
	v_and_b32_e32 v33, 0xffff0000, v234
	v_lshlrev_b32_e32 v32, 16, v234
	v_and_b32_e32 v41, 0xffff0000, v235
	v_lshlrev_b32_e32 v40, 16, v235
	v_and_b32_e32 v35, 0xffff0000, v236
	v_lshlrev_b32_e32 v34, 16, v236
	v_mul_f32_e32 v16, 0xbfb8aa3b, v30
	v_mul_f32_e32 v23, 0xbfb8aa3b, v31
	v_mul_f32_e32 v29, 0xbfb8aa3b, v38
	v_mul_f32_e32 v36, 0xbfb8aa3b, v39
	v_and_b32_e32 v43, 0xffff0000, v237
	v_lshlrev_b32_e32 v42, 16, v237
	v_mul_f32_e32 v37, 0xbfb8aa3b, v32
	v_mul_f32_e32 v65, 0xbfb8aa3b, v33
	v_mul_f32_e32 v66, 0xbfb8aa3b, v40
	v_mul_f32_e32 v67, 0xbfb8aa3b, v41
	v_exp_f32_e32 v16, v16
	v_exp_f32_e32 v23, v23
	v_exp_f32_e32 v29, v29
	v_exp_f32_e32 v36, v36
	v_mul_f32_e32 v68, 0xbfb8aa3b, v34
	v_mul_f32_e32 v69, 0xbfb8aa3b, v35
	v_mul_f32_e32 v70, 0xbfb8aa3b, v42
	v_mul_f32_e32 v71, 0xbfb8aa3b, v43
	v_exp_f32_e32 v37, v37
	v_exp_f32_e32 v65, v65
	v_exp_f32_e32 v66, v66
	v_exp_f32_e32 v67, v67
	v_exp_f32_e32 v68, v68
	v_exp_f32_e32 v69, v69
	v_exp_f32_e32 v70, v70
	v_exp_f32_e32 v71, v71
	v_add_f32_e32 v16, 1.0, v16
	v_add_f32_e32 v23, 1.0, v23
	v_add_f32_e32 v29, 1.0, v29
	v_add_f32_e32 v72, 1.0, v36
	v_add_f32_e32 v73, 1.0, v37
	v_add_f32_e32 v65, 1.0, v65
	v_add_f32_e32 v74, 1.0, v66
	v_add_f32_e32 v75, 1.0, v67
	v_rcp_f32_e32 v36, v16
	v_rcp_f32_e32 v37, v23
	v_rcp_f32_e32 v66, v29
	v_rcp_f32_e32 v67, v72
	v_add_f32_e32 v76, 1.0, v68
	v_add_f32_e32 v77, 1.0, v69
	v_add_f32_e32 v78, 1.0, v70
	v_add_f32_e32 v79, 1.0, v71
	v_rcp_f32_e32 v68, v73
	v_rcp_f32_e32 v69, v65
	v_rcp_f32_e32 v70, v74
	v_rcp_f32_e32 v71, v75
	v_rcp_f32_e32 v72, v76
	v_rcp_f32_e32 v73, v77
	v_rcp_f32_e32 v74, v78
	v_rcp_f32_e32 v75, v79
	v_pk_mul_f32 v[30:31], v[36:37], v[30:31]
	v_pk_mul_f32 v[36:37], v[66:67], v[38:39]
	v_pk_mul_f32 v[32:33], v[68:69], v[32:33]
	v_pk_mul_f32 v[38:39], v[70:71], v[40:41]
	v_pk_mul_f32 v[8:9], v[8:9], v[30:31]
	v_pk_mul_f32 v[10:11], v[10:11], v[36:37]
	v_pk_mul_f32 v[12:13], v[12:13], v[32:33]
	v_pk_mul_f32 v[14:15], v[14:15], v[38:39]
	v_cvt_pk_bf16_f32 v8, v8, v9
	v_cvt_pk_bf16_f32 v9, v10, v11
	v_pk_mul_f32 v[34:35], v[72:73], v[34:35]
	v_cvt_pk_bf16_f32 v10, v12, v13
	v_cvt_pk_bf16_f32 v11, v14, v15
	global_store_dwordx2 v[26:27], v[8:9], off
	global_store_dwordx2 v[26:27], v[10:11], off offset:32
	v_pk_mul_f32 v[6:7], v[28:29], v[6:7] op_sel_hi:[0,1]
	v_pk_mul_f32 v[8:9], v[74:75], v[42:43]
	v_pk_mul_f32 v[4:5], v[4:5], v[34:35]
	v_pk_mul_f32 v[6:7], v[6:7], v[8:9]
	v_cvt_pk_bf16_f32 v4, v4, v5
	v_cvt_pk_bf16_f32 v5, v6, v7
	global_store_dwordx2 v[26:27], v[4:5], off offset:64
	v_lshlrev_b32_e32 v4, 16, v238
	v_mul_f32_e32 v5, 0xbfb8aa3b, v4
	v_exp_f32_e32 v6, v5
	v_and_b32_e32 v5, 0xffff0000, v238
	v_mul_f32_e32 v7, 0xbfb8aa3b, v5
	v_exp_f32_e32 v7, v7
	v_and_b32_e32 v9, 0xffff0000, v239
	v_lshlrev_b32_e32 v8, 16, v239
	v_add_f32_e32 v6, 1.0, v6
	v_add_f32_e32 v7, 1.0, v7
	v_mul_f32_e32 v10, 0xbfb8aa3b, v8
	v_mul_f32_e32 v11, 0xbfb8aa3b, v9
	v_rcp_f32_e32 v6, v6
	v_rcp_f32_e32 v7, v7
	v_exp_f32_e32 v10, v10
	v_exp_f32_e32 v11, v11
	v_pk_mul_f32 v[0:1], v[28:29], v[0:1] op_sel_hi:[0,1]
	v_pk_mul_f32 v[4:5], v[6:7], v[4:5]
	v_add_f32_e32 v6, 1.0, v10
	v_add_f32_e32 v7, 1.0, v11
	v_rcp_f32_e32 v6, v6
	v_rcp_f32_e32 v7, v7
	v_pk_mul_f32 v[0:1], v[0:1], v[4:5]
	v_pk_mul_f32 v[2:3], v[28:29], v[2:3] op_sel_hi:[0,1]
	v_cvt_pk_bf16_f32 v0, v0, v1
	v_pk_mul_f32 v[4:5], v[6:7], v[8:9]
	s_nop 0
	v_pk_mul_f32 v[2:3], v[2:3], v[4:5]
	s_nop 0
	v_cvt_pk_bf16_f32 v1, v2, v3
	global_store_dwordx2 v[26:27], v[0:1], off offset:96

; __device__ __forceinline__ unsigned cvt_pk_bf16(float lo, float hi) { const f32v2_t v = {lo, hi}; const bf16v2_t r = __builtin_convertvector(v, bf16v2_t); return __builtin_bit_cast(unsigned, r); }
; __device__ __forceinline__ float bf2f(short b) { return __uint_as_float(((unsigned)(unsigned short)b) << 16); }
; __device__ __forceinline__ void attn_items(const Params& p, LAS unsigned char* lds, int ai0, int aistride) {
;     ...
;             if (qt < nqt) {
;                 const int r = qt / ntt, tok0 = 16 * (qt % ntt), hh = g * 4 + r;
;                 const size_t qrow = (size_t)(row0 + tok0 + fr);
;                 bf16x8 Qf[2];
;                 {
;                     const bf16x8 r0 = *(const bf16x8*)(Z + qrow * NZ + ZC_AQ + hh * 64 + 8 * fq), r1 = *(const bf16x8*)(Z + qrow * NZ + ZC_AQ + hh * 64 + 32 + 8 * fq);
;                     float q0[8], q1[8]; float ss = 0.f;
; #pragma unroll
;                     for (int e = 0; e < 8; ++e) { q0[e] = bf2f(r0[e]); q1[e] = bf2f(r1[e]); ss += q0[e] * q0[e] + q1[e] * q1[e]; }
;                     ss += __shfl_xor(ss, 16); ss += __shfl_xor(ss, 32);
;                     const float rq = rsqrtf(ss * (1.0f / 64.0f) + 1e-6f) * 0.125f;
;                     const float4 na = *(const float4*)(p.in[9] + 8 * fq), nb = *(const float4*)(p.in[9] + 8 * fq + 4), nc = *(const float4*)(p.in[9] + 32 + 8 * fq), nd = *(const float4*)(p.in[9] + 32 + 8 * fq + 4);
;                     u32x4 w0, w1;
;                     w0.x = cvt_pk_bf16(q0[0] * rq * na.x, q0[1] * rq * na.y); w0.y = cvt_pk_bf16(q0[2] * rq * na.z, q0[3] * rq * na.w);
;                     w0.z = cvt_pk_bf16(q0[4] * rq * nb.x, q0[5] * rq * nb.y); w0.w = cvt_pk_bf16(q0[6] * rq * nb.z, q0[7] * rq * nb.w);
;                     w1.x = cvt_pk_bf16(q1[0] * rq * nc.x, q1[1] * rq * nc.y); w1.y = cvt_pk_bf16(q1[2] * rq * nc.z, q1[3] * rq * nc.w);
;                     w1.z = cvt_pk_bf16(q1[4] * rq * nd.x, q1[5] * rq * nd.y); w1.w = cvt_pk_bf16(q1[6] * rq * nd.z, q1[7] * rq * nd.w);
;                     Qf[0] = __builtin_bit_cast(bf16x8, w0); Qf[1] = __builtin_bit_cast(bf16x8, w1);
;                 }
;                 const float slope = exp2f(-(float)(hh + 1));
;                 const float sink = p.in[11][hh];
;                 const int qoff = samp ? (tok0 + fr + 128) : ((nkc - 1) * 64 + tok0 + fr);
;                 f32x4 s[12]; float mx = sink;
.LBB0_546:
	v_or_b32_e32 v0, s4, v45
	v_cmp_gt_u32_e32 vcc, s76, v0
	s_and_saveexec_b64 s[66:67], vcc
	s_cbranch_execz .LBB0_545
	v_lshrrev_b32_e32 v1, s77, v0
	v_and_b32_e32 v0, s78, v0
	v_lshlrev_b32_e32 v14, 4, v0
	v_add_u32_e32 v28, s79, v1
	v_add_u32_e32 v26, v63, v14
	v_mov_b64_e32 v[0:1], s[14:15]
	v_mad_i64_i32 v[0:1], s[0:1], v26, s68, v[0:1]
	v_lshlrev_b32_e32 v16, 7, v28
	v_lshl_add_u64 v[24:25], v[0:1], 0, v[16:17]
	v_mov_b32_e32 v23, v17
	v_lshl_add_u64 v[4:5], v[24:25], 0, v[22:23]
	global_load_dwordx4 v[0:3], v[4:5], off offset:64
	s_nop 0
	global_load_dwordx4 v[4:7], v[4:5], off
	s_nop 0
	global_load_dwordx4 v[8:11], v[20:21], off offset:144
	global_load_dwordx4 v[30:33], v[20:21], off offset:128
	global_load_dwordx4 v[34:37], v[20:21], off offset:16
	global_load_dwordx4 v[38:41], v[20:21], off
	v_and_b32_e32 v13, 64, v58
	v_xor_b32_e32 v12, 16, v58
	v_add_u32_e32 v13, 64, v13
	v_xor_b32_e32 v15, 32, v58
	v_mov_b32_e32 v29, v17
	v_cmp_lt_i32_e32 vcc, v12, v13
	v_add_u32_e32 v23, 1, v28
	ds_read_b128 v[66:69], v61
	ds_read_b128 v[70:73], v61 offset:64
	ds_read_b128 v[74:77], v61 offset:2304
	ds_read_b128 v[78:81], v61 offset:2368
	v_cndmask_b32_e32 v16, v58, v12, vcc
	v_cmp_lt_i32_e32 vcc, v15, v13
	v_lshl_add_u64 v[12:13], v[28:29], 2, s[74:75]
	v_add_u32_e32 v29, v14, v64
	v_cvt_f32_u32_e32 v14, v23
	global_load_dword v23, v[12:13], off
	v_lshlrev_b32_e32 v27, 2, v16
	v_cndmask_b32_e32 v15, v58, v15, vcc
	v_lshlrev_b32_e32 v16, 2, v15
	v_cmp_lt_f32_e64 s[4:5], s70, v14
	v_sub_u32_e32 v15, v29, v18
	v_lshlrev_b32_e32 v240, 1, v18
	v_mov_b32_e32 v241, 0
	v_lshl_add_u64 v[240:241], v[24:25], 0, v[240:241]
	global_load_dwordx2 v[232:233], v[240:241], off offset:1536
	global_load_dwordx2 v[234:235], v[240:241], off offset:1568
	global_load_dwordx2 v[236:237], v[240:241], off offset:1600
	global_load_dwordx2 v[238:239], v[240:241], off offset:1632
	s_waitcnt vmcnt(0)
	v_and_b32_e32 v43, 0xffff0000, v1
	v_lshlrev_b32_e32 v42, 16, v1
	v_and_b32_e32 v1, 0xffff0000, v0
	v_lshlrev_b32_e32 v0, 16, v0
	v_and_b32_e32 v85, 0xffff0000, v5
	v_lshlrev_b32_e32 v84, 16, v5
	v_and_b32_e32 v5, 0xffff0000, v4
	v_lshlrev_b32_e32 v4, 16, v4
	v_pk_mul_f32 v[92:93], v[0:1], v[0:1]
	v_pk_mul_f32 v[90:91], v[42:43], v[42:43]
	v_pk_fma_f32 v[92:93], v[4:5], v[4:5], v[92:93]
	v_and_b32_e32 v13, 0xffff0000, v3
	v_lshlrev_b32_e32 v12, 16, v3
	v_and_b32_e32 v3, 0xffff0000, v2
	v_lshlrev_b32_e32 v2, 16, v2
	v_pk_fma_f32 v[90:91], v[84:85], v[84:85], v[90:91]
	v_add_f32_e32 v65, v92, v93
	v_and_b32_e32 v83, 0xffff0000, v7
	v_lshlrev_b32_e32 v82, 16, v7
	v_and_b32_e32 v7, 0xffff0000, v6
	v_lshlrev_b32_e32 v6, 16, v6
	v_pk_mul_f32 v[88:89], v[2:3], v[2:3]
	v_add_f32_e32 v65, v90, v65
	v_pk_fma_f32 v[88:89], v[6:7], v[6:7], v[88:89]
	v_add_f32_e32 v65, v91, v65
	v_pk_mul_f32 v[86:87], v[12:13], v[12:13]
	v_add_f32_e32 v65, v88, v65
	v_pk_fma_f32 v[86:87], v[82:83], v[82:83], v[86:87]
	v_add_f32_e32 v65, v89, v65
	v_add_f32_e32 v65, v86, v65
	v_add_f32_e32 v65, v87, v65
	ds_bpermute_b32 v86, v27, v65
	v_add_u32_e32 v87, v29, v46
	v_cvt_f32_i32_e32 v90, v87
	v_add_u32_e32 v87, -2, v15
	v_cvt_f32_i32_e32 v92, v87
	s_waitcnt lgkmcnt(0)
	v_add_f32_e32 v65, v65, v86
	ds_bpermute_b32 v86, v16, v65
	v_add_u32_e32 v91, -3, v15
	v_cvt_f32_i32_e32 v89, v15
	v_sub_u32_e32 v88, v29, v47
	v_cvt_f32_i32_e32 v88, v88
	s_waitcnt lgkmcnt(0)
; #define LAS __attribute__((address_space(3)))
; __device__ __forceinline__ void attn_items(const Params& p, LAS unsigned char* lds, int ai0, int aistride) {
;     ...
;                     for (int e = 0; e < 8; ++e) { q0[e] = bf2f(r0[e]); q1[e] = bf2f(r1[e]); ss += q0[e] * q0[e] + q1[e] * q1[e]; }
;                     ss += __shfl_xor(ss, 16); ss += __shfl_xor(ss, 32);
;                     const float rq = rsqrtf(ss * (1.0f / 64.0f) + 1e-6f) * 0.125f;
;                     const float4 na = *(const float4*)(p.in[9] + 8 * fq), nb = *(const float4*)(p.in[9] + 8 * fq + 4), nc = *(const float4*)(p.in[9] + 32 + 8 * fq), nd = *(const float4*)(p.in[9] + 32 + 8 * fq + 4);
;                     u32x4 w0, w1;
;                     w0.x = cvt_pk_bf16(q0[0] * rq * na.x, q0[1] * rq * na.y); w0.y = cvt_pk_bf16(q0[2] * rq * na.z, q0[3] * rq * na.w);
;                     w0.z = cvt_pk_bf16(q0[4] * rq * nb.x, q0[5] * rq * nb.y); w0.w = cvt_pk_bf16(q0[6] * rq * nb.z, q0[7] * rq * nb.w);
;                     w1.x = cvt_pk_bf16(q1[0] * rq * nc.x, q1[1] * rq * nc.y); w1.y = cvt_pk_bf16(q1[2] * rq * nc.z, q1[3] * rq * nc.w);
;                     w1.z = cvt_pk_bf16(q1[4] * rq * nd.x, q1[5] * rq * nd.y); w1.w = cvt_pk_bf16(q1[6] * rq * nd.z, q1[7] * rq * nd.w);
;                     Qf[0] = __builtin_bit_cast(bf16x8, w0); Qf[1] = __builtin_bit_cast(bf16x8, w1);
;                 }
;                 const float slope = exp2f(-(float)(hh + 1));
;                 const float sink = p.in[11][hh];
;                 const int qoff = samp ? (tok0 + fr + 128) : ((nkc - 1) * 64 + tok0 + fr);
;                 f32x4 s[12]; float mx = sink;
; #pragma unroll
;                 for (int kt = 0; kt < 12; ++kt) {
;                     if (kt < nkt) {
;                         f32x4 acc = {0.f, 0.f, 0.f, 0.f};
; #pragma unroll
;                         for (int kk = 0; kk < 2; ++kk) { const bf16x8 a = *(const LAS bf16x8*)(K_s + (16 * kt + fr) * 72 + 32 * kk + 8 * fq); acc = mfma16(a, Qf[kk], acc); }
; #pragma unroll
;                         for (int jj = 0; jj < 4; ++jj) { const int key = 16 * kt + 4 * fq + jj; const bool valid = !samp || key < 144;
;                             const float sv = valid ? acc[jj] - slope * fabsf((float)(qoff - key)) : -1e30f; s[kt][jj] = sv; mx = fmaxf(mx, sv); }
;                     } else { s[kt] = (f32x4){-1e30f, -1e30f, -1e30f, -1e30f}; }
;                 }
	v_add_f32_e32 v65, v65, v86
	v_fmamk_f32 v65, v65, 0x3c800000, v57
	v_mul_f32_e32 v86, 0x4b800000, v65
	v_cmp_gt_f32_e32 vcc, s69, v65
	s_nop 1
	v_cndmask_b32_e32 v65, v65, v86, vcc
	v_rsq_f32_e32 v65, v65
	v_cndmask_b32_e64 v86, 0, v59, s[4:5]
	v_sub_f32_e32 v14, v86, v14
	v_exp_f32_e32 v93, v14
	v_mul_f32_e32 v14, 0x45800000, v65
	v_cndmask_b32_e32 v14, v65, v14, vcc
	v_mul_f32_e32 v14, 0x3e000000, v14
	v_pk_mul_f32 v[4:5], v[14:15], v[4:5] op_sel_hi:[0,1]
	v_pk_mul_f32 v[84:85], v[14:15], v[84:85] op_sel_hi:[0,1]
	v_pk_mul_f32 v[6:7], v[14:15], v[6:7] op_sel_hi:[0,1]
	v_pk_mul_f32 v[82:83], v[14:15], v[82:83] op_sel_hi:[0,1]
	v_pk_mul_f32 v[0:1], v[14:15], v[0:1] op_sel_hi:[0,1]
	v_pk_mul_f32 v[86:87], v[14:15], v[2:3] op_sel_hi:[0,1]
	v_pk_mul_f32 v[2:3], v[38:39], v[4:5]
	v_pk_mul_f32 v[4:5], v[40:41], v[84:85]
	v_pk_mul_f32 v[6:7], v[34:35], v[6:7]
	v_pk_mul_f32 v[34:35], v[36:37], v[82:83]
	v_pk_mul_f32 v[42:43], v[14:15], v[42:43] op_sel_hi:[0,1]
	v_pk_mul_f32 v[36:37], v[30:31], v[0:1]
	v_cvt_pk_bf16_f32 v0, v2, v3
	v_cvt_pk_bf16_f32 v1, v4, v5
	v_cvt_pk_bf16_f32 v2, v6, v7
	v_cvt_pk_bf16_f32 v3, v34, v35
	v_pk_mul_f32 v[38:39], v[32:33], v[42:43]
	v_pk_mul_f32 v[12:13], v[14:15], v[12:13] op_sel_hi:[0,1]
	v_mfma_f32_16x16x32_bf16 v[30:33], v[66:69], v[0:3], 0
	v_mul_f32_e64 v6, v8, v86
	v_mul_f32_e64 v7, v9, v87
	v_pk_mul_f32 v[12:13], v[10:11], v[12:13]
	v_cvt_pk_bf16_f32 v4, v36, v37
	v_cvt_pk_bf16_f32 v5, v38, v39
	v_cvt_pk_bf16_f32 v6, v6, v7
	v_cvt_pk_bf16_f32 v7, v12, v13
	v_mfma_f32_16x16x32_bf16 v[8:11], v[74:77], v[0:3], 0
	v_cvt_f32_i32_e32 v12, v91
	v_cndmask_b32_e64 v13, 0, v60, s[4:5]
	v_ldexp_f32 v14, v93, v13
	v_mfma_f32_16x16x32_bf16 v[30:33], v[70:73], v[4:7], v[30:33]
	v_subrev_u32_e32 v34, 19, v15
	v_subrev_u32_e32 v13, 18, v15
	v_cvt_f32_i32_e32 v38, v34
	v_mfma_f32_16x16x32_bf16 v[8:11], v[78:81], v[4:7], v[8:11]
	ds_read_b128 v[34:37], v61 offset:4672
	s_nop 2
	v_fma_f32 v78, -v14, |v89|, v30
	v_fma_f32 v74, -v14, |v90|, v31
	v_fma_f32 v70, -v14, |v92|, v32
	v_fma_f32 v69, -v14, |v12|, v33
	ds_read_b128 v[30:33], v61 offset:4608
	v_subrev_u32_e32 v12, 17, v15
	v_cvt_f32_i32_e32 v12, v12
	v_cvt_f32_i32_e32 v13, v13
	v_fma_f32 v66, -v14, |v88|, v8
	v_max3_f32 v8, v23, v78, v74
	v_max3_f32 v8, v8, v70, v69
	v_fma_f32 v71, -v14, |v12|, v9
	v_max3_f32 v12, v8, v66, v71
	v_fma_f32 v67, -v14, |v13|, v10
	v_fma_f32 v65, -v14, |v38|, v11
	s_waitcnt lgkmcnt(0)
	v_mfma_f32_16x16x32_bf16 v[8:11], v[30:33], v[0:3], 0
	v_sub_u32_e32 v13, v29, v48
	v_cvt_f32_i32_e32 v13, v13
	ds_read_b128 v[30:33], v61 offset:6912
	v_mfma_f32_16x16x32_bf16 v[8:11], v[34:37], v[4:7], v[8:11]
	v_subrev_u32_e32 v34, 35, v15
	v_cvt_f32_i32_e32 v38, v34
	ds_read_b128 v[34:37], v61 offset:6976
	v_max3_f32 v12, v12, v67, v65
	s_andn2_b64 vcc, exec, s[26:27]
	s_nop 2
	v_fma_f32 v68, -v14, |v13|, v8
	v_subrev_u32_e32 v8, 33, v15
	v_subrev_u32_e32 v13, 34, v15
	v_cvt_f32_i32_e32 v8, v8
	v_cvt_f32_i32_e32 v13, v13
	v_fma_f32 v72, -v14, |v38|, v11
	v_fma_f32 v79, -v14, |v8|, v9
	v_fma_f32 v75, -v14, |v13|, v10
	s_waitcnt lgkmcnt(1)
	v_mfma_f32_16x16x32_bf16 v[8:11], v[30:33], v[0:3], 0
	v_sub_u32_e32 v13, v29, v49
	v_cvt_f32_i32_e32 v13, v13
	v_subrev_u32_e32 v29, 51, v15
	s_waitcnt lgkmcnt(0)
	v_mfma_f32_16x16x32_bf16 v[8:11], v[34:37], v[4:7], v[8:11]
	v_cvt_f32_i32_e32 v29, v29
	v_max3_f32 v12, v12, v68, v79
	v_max3_f32 v12, v12, v75, v72
	s_nop 4
	v_fma_f32 v76, -v14, |v13|, v8
	v_subrev_u32_e32 v8, 49, v15
	v_cvt_f32_i32_e32 v8, v8
	v_subrev_u32_e32 v13, 50, v15
	v_cvt_f32_i32_e32 v13, v13
	v_fma_f32 v73, -v14, |v29|, v11
	v_fma_f32 v80, -v14, |v8|, v9
	v_max3_f32 v8, v12, v76, v80
	v_fma_f32 v77, -v14, |v13|, v10
	v_max3_f32 v29, v8, v77, v73
	v_cndmask_b32_e64 v8, 0, 1, s[26:27]
	v_cmp_ne_u32_e64 s[4:5], 1, v8
	v_mov_b32_e32 v8, 0xf149f2ca
	s_cbranch_vccnz .LBB0_550
	ds_read_b128 v[10:13], v61 offset:9216
	ds_read_b128 v[30:33], v61 offset:9280
	v_add_u32_e32 v9, 0xffffffbf, v15
	v_subrev_u32_e32 v34, 64, v15
	v_add_u32_e32 v35, 0xffffffbd, v15
	s_waitcnt lgkmcnt(1)
	v_mfma_f32_16x16x32_bf16 v[10:13], v[10:13], v[0:3], 0
	v_add_u32_e32 v36, 0xffffffbe, v15
	v_cvt_f32_i32_e32 v9, v9
	v_cvt_f32_i32_e32 v34, v34
	v_cvt_f32_i32_e32 v36, v36
	v_cvt_f32_i32_e32 v37, v35
	s_waitcnt lgkmcnt(0)
	v_mfma_f32_16x16x32_bf16 v[30:33], v[30:33], v[4:7], v[10:13]
	v_and_b32_e32 v35, 0x7fffffff, v9
	v_and_b32_e32 v34, 0x7fffffff, v34
	s_nop 0
	v_and_b32_e32 v11, 0x7fffffff, v37
	v_and_b32_e32 v10, 0x7fffffff, v36
	s_nop 2
	v_pk_fma_f32 v[12:13], v[14:15], v[34:35], v[30:31] op_sel_hi:[0,1,1] neg_lo:[1,0,0] neg_hi:[1,0,0]
	v_max3_f32 v9, v29, v12, v13
	v_pk_fma_f32 v[10:11], v[14:15], v[10:11], v[32:33] op_sel_hi:[0,1,1] neg_lo:[1,0,0] neg_hi:[1,0,0]
	v_max3_f32 v29, v9, v10, v11
	s_andn2_b64 vcc, exec, s[28:29]
	s_cbranch_vccz .LBB0_551

; #define PG8_STAGE(bufoff, gbase, voff) do { _Pragma("unroll") for (int _i = 0; _i < 2; ++_i) \
;         __builtin_amdgcn_global_load_lds((const unsigned*)((const char*)(gbase) + (voff)[_i]), (LAS unsigned*)(lds + (bufoff) + ldsw + _i * 8192), 16, 0, 0); } while (0)
; #define PG8_LDA(dst, b, h) do { _Pragma("unroll") for (int m = 0; m < 4; ++m) _Pragma("unroll") for (int k = 0; k < 2; ++k) dst[m][k] = *(const LAS bf16x8*)(lds + PG8_SA(b, h) + aoff + m * 2048 + k * 1024); } while (0)
; #define PG8_LDB(dst, b, h) do { _Pragma("unroll") for (int n = 0; n < 2; ++n) _Pragma("unroll") for (int k = 0; k < 2; ++k) dst[n][k] = *(const LAS bf16x8*)(lds + PG8_SB(b, h) + boff + n * 2048 + k * 1024); } while (0)
; #define PG8_MMA(ai, bj, At, Bt) do { __builtin_amdgcn_s_setprio(1); _Pragma("unroll") for (int m = 0; m < 4; ++m) _Pragma("unroll") for (int n = 0; n < 2; ++n) _Pragma("unroll") for (int k = 0; k < 2; ++k) \
;         acc[ai][bj][m][n] = __builtin_amdgcn_mfma_f32_16x16x32_bf16(Bt[n][k], At[m][k], acc[ai][bj][m][n], 0, 0, 0); __builtin_amdgcn_s_setprio(0); } while (0)
; #define PG8_WAIT_L(n) asm volatile("s_waitcnt lgkmcnt(" #n ")" ::: "memory")
; #define PG8_BAR __builtin_amdgcn_s_barrier()
; #define PG8_SCHED __builtin_amdgcn_sched_barrier(0)
; template <class Epi>
; __device__ __forceinline__ void gemm_phase(LAS unsigned char* lds, const Gemm g, const StaticOrder& S, const Epi& E) {
;     ...
;             PG8_LDB(B0, 0, 0); PG8_SCHED; PG8_LDA(At, 0, 0); PG8_STAGE(PG8_SA(1, 1), a1 + hstepA, voffA);
;             PG8_WAIT_L(8); PG8_BAR; PG8_WAIT_L(0); PG8_MMA(0, 0, At, B0); PG8_BAR; PG8_SCHED;
;             PG8_LDB(B1, 0, 1); PG8_STAGE(PG8_SB(0, 0), b2, voffB);
;             PG8_BAR; PG8_WAIT_L(0); PG8_MMA(0, 1, At, B1); PG8_BAR;
;             PG8_LDA(At, 0, 1); PG8_STAGE(PG8_SA(0, 0), a2, voffA);
;             PG8_BAR; PG8_WAIT_L(0); PG8_MMA(1, 0, At, B0); PG8_BAR; PG8_SCHED;
.LBB0_862:
	ds_read_b128 v[128:131], v161
	ds_read_b128 v[148:151], v161 offset:1024
	ds_read_b128 v[152:155], v161 offset:2048
	ds_read_b128 v[166:169], v161 offset:3072
	s_add_u32 s52, s46, 0xfffc0080
	s_addc_u32 s53, s47, -1
	s_cmp_eq_u32 s69, 12
	s_cselect_b32 s55, s0, s53
	s_cselect_b32 s54, s1, s52
	s_cselect_b32 s53, s7, s39
	s_cselect_b32 s52, s9, s37
	v_lshl_add_u64 v[182:183], s[46:47], 0, v[140:141]
	s_add_i32 m0, s34, 0xc000
	ds_read_b128 v[170:173], v162
	ds_read_b128 v[174:177], v162 offset:1024
	ds_read_b128 v[178:181], v162 offset:2048
	ds_read_b128 v[186:189], v162 offset:3072
	ds_read_b128 v[190:193], v162 offset:4096
	ds_read_b128 v[194:197], v162 offset:5120
	ds_read_b128 v[198:201], v162 offset:6144
	ds_read_b128 v[202:205], v162 offset:7168
	global_load_lds_dwordx4 v[182:183], off
	v_lshl_add_u64 v[182:183], s[46:47], 0, v[142:143]
	s_add_i32 m0, s34, 0xe000
	s_nop 0
	global_load_lds_dwordx4 v[182:183], off
	s_waitcnt lgkmcnt(8)
	s_barrier
	s_waitcnt lgkmcnt(0)
	s_setprio 1
	s_waitcnt lgkmcnt(0)
	v_mfma_f32_16x16x32_bf16 v[124:127], v[128:131], v[170:173], v[124:127]
	v_mfma_f32_16x16x32_bf16 v[120:123], v[152:155], v[170:173], v[120:123]
	v_mfma_f32_16x16x32_bf16 v[108:111], v[128:131], v[178:181], v[108:111]
	v_mfma_f32_16x16x32_bf16 v[104:107], v[152:155], v[178:181], v[104:107]
	v_mfma_f32_16x16x32_bf16 v[92:95], v[128:131], v[190:193], v[92:95]
	v_mfma_f32_16x16x32_bf16 v[88:91], v[152:155], v[190:193], v[88:91]
	v_mfma_f32_16x16x32_bf16 v[76:79], v[128:131], v[198:201], v[76:79]
	v_mfma_f32_16x16x32_bf16 v[72:75], v[152:155], v[198:201], v[72:75]
	v_mfma_f32_16x16x32_bf16 v[124:127], v[148:151], v[174:177], v[124:127]
	v_mfma_f32_16x16x32_bf16 v[120:123], v[166:169], v[174:177], v[120:123]
	v_mfma_f32_16x16x32_bf16 v[108:111], v[148:151], v[186:189], v[108:111]
	v_mfma_f32_16x16x32_bf16 v[104:107], v[166:169], v[186:189], v[104:107]
	v_mfma_f32_16x16x32_bf16 v[92:95], v[148:151], v[194:197], v[92:95]
	v_mfma_f32_16x16x32_bf16 v[88:91], v[166:169], v[194:197], v[88:91]
	v_mfma_f32_16x16x32_bf16 v[76:79], v[148:151], v[202:205], v[76:79]
	v_mfma_f32_16x16x32_bf16 v[72:75], v[166:169], v[202:205], v[72:75]
	s_setprio 0
	s_barrier
	s_add_i32 s70, s66, s31
	v_lshl_add_u64 v[182:183], s[52:53], 0, v[134:135]
	s_mov_b32 m0, s70
	ds_read_b128 v[206:209], v163
	ds_read_b128 v[210:213], v163 offset:1024
	ds_read_b128 v[214:217], v163 offset:2048
	ds_read_b128 v[218:221], v163 offset:3072
	global_load_lds_dwordx4 v[182:183], off
	v_lshl_add_u64 v[222:223], s[52:53], 0, v[138:139]
	s_add_i32 m0, s70, 0x2000
	s_nop 0
	global_load_lds_dwordx4 v[222:223], off
	s_barrier
	s_waitcnt lgkmcnt(0)
	s_setprio 1
	s_waitcnt lgkmcnt(0)
	v_mfma_f32_16x16x32_bf16 v[116:119], v[206:209], v[170:173], v[116:119]
	v_mfma_f32_16x16x32_bf16 v[112:115], v[214:217], v[170:173], v[112:115]
	v_mfma_f32_16x16x32_bf16 v[100:103], v[206:209], v[178:181], v[100:103]
	v_mfma_f32_16x16x32_bf16 v[96:99], v[214:217], v[178:181], v[96:99]
	v_mfma_f32_16x16x32_bf16 v[84:87], v[206:209], v[190:193], v[84:87]
	v_mfma_f32_16x16x32_bf16 v[80:83], v[214:217], v[190:193], v[80:83]
	v_mfma_f32_16x16x32_bf16 v[68:71], v[206:209], v[198:201], v[68:71]
	v_mfma_f32_16x16x32_bf16 v[64:67], v[214:217], v[198:201], v[64:67]
	v_mfma_f32_16x16x32_bf16 v[116:119], v[210:213], v[174:177], v[116:119]
	v_mfma_f32_16x16x32_bf16 v[112:115], v[218:221], v[174:177], v[112:115]
	v_mfma_f32_16x16x32_bf16 v[100:103], v[210:213], v[186:189], v[100:103]
	v_mfma_f32_16x16x32_bf16 v[96:99], v[218:221], v[186:189], v[96:99]
	v_mfma_f32_16x16x32_bf16 v[84:87], v[210:213], v[194:197], v[84:87]
	v_mfma_f32_16x16x32_bf16 v[80:83], v[218:221], v[194:197], v[80:83]
	v_mfma_f32_16x16x32_bf16 v[68:71], v[210:213], v[202:205], v[68:71]
	v_mfma_f32_16x16x32_bf16 v[64:67], v[218:221], v[202:205], v[64:67]
	s_setprio 0
	s_mov_b32 m0, s34
	v_lshl_add_u64 v[224:225], s[54:55], 0, v[132:133]
	s_barrier
	ds_read_b128 v[170:173], v162 offset:16384
	ds_read_b128 v[174:177], v162 offset:17408
	ds_read_b128 v[178:181], v162 offset:18432
	ds_read_b128 v[186:189], v162 offset:19456
	ds_read_b128 v[190:193], v162 offset:20480
	ds_read_b128 v[194:197], v162 offset:21504
	ds_read_b128 v[198:201], v162 offset:22528
	ds_read_b128 v[202:205], v162 offset:23552
	global_load_lds_dwordx4 v[224:225], off
	v_lshl_add_u64 v[226:227], s[54:55], 0, v[136:137]
	s_mov_b32 m0, s35
	s_nop 0
	global_load_lds_dwordx4 v[226:227], off
	s_barrier
	s_waitcnt lgkmcnt(0)
	s_setprio 1
	s_waitcnt lgkmcnt(0)
	v_mfma_f32_16x16x32_bf16 v[60:63], v[128:131], v[170:173], v[60:63]
	v_mfma_f32_16x16x32_bf16 v[56:59], v[152:155], v[170:173], v[56:59]
	v_mfma_f32_16x16x32_bf16 v[44:47], v[128:131], v[178:181], v[44:47]
	v_mfma_f32_16x16x32_bf16 v[40:43], v[152:155], v[178:181], v[40:43]
	v_mfma_f32_16x16x32_bf16 v[28:31], v[128:131], v[190:193], v[28:31]
	v_mfma_f32_16x16x32_bf16 v[24:27], v[152:155], v[190:193], v[24:27]
	v_mfma_f32_16x16x32_bf16 v[12:15], v[128:131], v[198:201], v[12:15]
	v_mfma_f32_16x16x32_bf16 v[8:11], v[152:155], v[198:201], v[8:11]
	v_mfma_f32_16x16x32_bf16 v[60:63], v[148:151], v[174:177], v[60:63]
	v_mfma_f32_16x16x32_bf16 v[56:59], v[166:169], v[174:177], v[56:59]
	v_mfma_f32_16x16x32_bf16 v[44:47], v[148:151], v[186:189], v[44:47]
	v_mfma_f32_16x16x32_bf16 v[40:43], v[166:169], v[186:189], v[40:43]
	v_mfma_f32_16x16x32_bf16 v[28:31], v[148:151], v[194:197], v[28:31]
	v_mfma_f32_16x16x32_bf16 v[24:27], v[166:169], v[194:197], v[24:27]
	v_mfma_f32_16x16x32_bf16 v[12:15], v[148:151], v[202:205], v[12:15]
	v_mfma_f32_16x16x32_bf16 v[8:11], v[166:169], v[202:205], v[8:11]
	s_setprio 0
	s_barrier
; #define PG8_STAGE(bufoff, gbase, voff) do { _Pragma("unroll") for (int _i = 0; _i < 2; ++_i) \
;         __builtin_amdgcn_global_load_lds((const unsigned*)((const char*)(gbase) + (voff)[_i]), (LAS unsigned*)(lds + (bufoff) + ldsw + _i * 8192), 16, 0, 0); } while (0)
; #define PG8_LDA(dst, b, h) do { _Pragma("unroll") for (int m = 0; m < 4; ++m) _Pragma("unroll") for (int k = 0; k < 2; ++k) dst[m][k] = *(const LAS bf16x8*)(lds + PG8_SA(b, h) + aoff + m * 2048 + k * 1024); } while (0)
; #define PG8_LDB(dst, b, h) do { _Pragma("unroll") for (int n = 0; n < 2; ++n) _Pragma("unroll") for (int k = 0; k < 2; ++k) dst[n][k] = *(const LAS bf16x8*)(lds + PG8_SB(b, h) + boff + n * 2048 + k * 1024); } while (0)
; #define PG8_MMA(ai, bj, At, Bt) do { __builtin_amdgcn_s_setprio(1); _Pragma("unroll") for (int m = 0; m < 4; ++m) _Pragma("unroll") for (int n = 0; n < 2; ++n) _Pragma("unroll") for (int k = 0; k < 2; ++k) \
;         acc[ai][bj][m][n] = __builtin_amdgcn_mfma_f32_16x16x32_bf16(Bt[n][k], At[m][k], acc[ai][bj][m][n], 0, 0, 0); __builtin_amdgcn_s_setprio(0); } while (0)
; #define PG8_WAIT_V(n) asm volatile("s_waitcnt vmcnt(" #n ")" ::: "memory")
; #define PG8_WAIT_L(n) asm volatile("s_waitcnt lgkmcnt(" #n ")" ::: "memory")
; #define PG8_BAR __builtin_amdgcn_s_barrier()
; #define PG8_SCHED __builtin_amdgcn_sched_barrier(0)
; template <class Epi>
; __device__ __forceinline__ void gemm_phase(LAS unsigned char* lds, const Gemm g, const StaticOrder& S, const Epi& E) {
;     ...
;             PG8_STAGE(PG8_SB(0, 1), b2 + hstepB, voffB);
;             PG8_WAIT_V(6); PG8_BAR; PG8_MMA(1, 1, At, B1); PG8_BAR;
;             PG8_LDB(B0, 1, 0); PG8_SCHED; PG8_LDA(At, 1, 0); PG8_STAGE(PG8_SA(0, 1), a2 + hstepA, voffA);
;             PG8_WAIT_L(8); PG8_BAR; PG8_WAIT_L(0); PG8_MMA(0, 0, At, B0); PG8_BAR; PG8_SCHED;
;             PG8_LDB(B1, 1, 1); PG8_STAGE(PG8_SB(1, 0), b3, voffB);
;             PG8_BAR; PG8_WAIT_L(0); PG8_MMA(0, 1, At, B1); PG8_BAR;
;             PG8_LDA(At, 1, 1); PG8_STAGE(PG8_SA(1, 0), a3, voffA);
	s_add_u32 s70, s52, 0x40000
	s_addc_u32 s71, s53, 0
	s_add_i32 s72, s67, s31
	v_lshl_add_u64 v[128:129], s[70:71], 0, v[134:135]
	s_mov_b32 m0, s72
	s_nop 0
	global_load_lds_dwordx4 v[128:129], off
	v_lshl_add_u64 v[128:129], s[70:71], 0, v[138:139]
	s_add_i32 m0, s72, 0x2000
	s_nop 0
	global_load_lds_dwordx4 v[128:129], off
	s_waitcnt vmcnt(6)
	s_barrier
	s_setprio 1
	v_mfma_f32_16x16x32_bf16 v[52:55], v[206:209], v[170:173], v[52:55]
	v_mfma_f32_16x16x32_bf16 v[48:51], v[214:217], v[170:173], v[48:51]
	v_mfma_f32_16x16x32_bf16 v[36:39], v[206:209], v[178:181], v[36:39]
	v_mfma_f32_16x16x32_bf16 v[32:35], v[214:217], v[178:181], v[32:35]
	v_mfma_f32_16x16x32_bf16 v[20:23], v[206:209], v[190:193], v[20:23]
	v_mfma_f32_16x16x32_bf16 v[16:19], v[214:217], v[190:193], v[16:19]
	v_mfma_f32_16x16x32_bf16 v[4:7], v[206:209], v[198:201], v[4:7]
	v_mfma_f32_16x16x32_bf16 v[0:3], v[214:217], v[198:201], v[0:3]
	v_mfma_f32_16x16x32_bf16 v[52:55], v[210:213], v[174:177], v[52:55]
	v_mfma_f32_16x16x32_bf16 v[48:51], v[218:221], v[174:177], v[48:51]
	v_mfma_f32_16x16x32_bf16 v[36:39], v[210:213], v[186:189], v[36:39]
	v_mfma_f32_16x16x32_bf16 v[32:35], v[218:221], v[186:189], v[32:35]
	v_mfma_f32_16x16x32_bf16 v[20:23], v[210:213], v[194:197], v[20:23]
	v_mfma_f32_16x16x32_bf16 v[16:19], v[218:221], v[194:197], v[16:19]
	v_mfma_f32_16x16x32_bf16 v[4:7], v[210:213], v[202:205], v[4:7]
	v_mfma_f32_16x16x32_bf16 v[0:3], v[218:221], v[202:205], v[0:3]
	s_setprio 0
	s_add_i32 s70, 0, 0x18000
	v_add_u32_e32 v165, s70, v159
	s_barrier
	ds_read_b128 v[128:131], v165
	ds_read_b128 v[148:151], v165 offset:1024
	ds_read_b128 v[152:155], v165 offset:2048
	ds_read_b128 v[166:169], v165 offset:3072
	s_add_u32 s54, s54, 0x40000
	s_addc_u32 s55, s55, 0
	s_mov_b32 m0, s56
	v_lshl_add_u64 v[206:207], s[54:55], 0, v[132:133]
	ds_read_b128 v[170:173], v162 offset:32768
	ds_read_b128 v[174:177], v162 offset:33792
	ds_read_b128 v[178:181], v162 offset:34816
	ds_read_b128 v[186:189], v162 offset:35840
	ds_read_b128 v[190:193], v162 offset:36864
	ds_read_b128 v[194:197], v162 offset:37888
	ds_read_b128 v[198:201], v162 offset:38912
	ds_read_b128 v[202:205], v162 offset:39936
	global_load_lds_dwordx4 v[206:207], off
	v_lshl_add_u64 v[206:207], s[54:55], 0, v[136:137]
	s_mov_b32 m0, s57
	s_nop 0
	global_load_lds_dwordx4 v[206:207], off
	s_waitcnt lgkmcnt(8)
	s_barrier
	s_waitcnt lgkmcnt(0)
	s_setprio 1
	s_waitcnt lgkmcnt(0)
	v_mfma_f32_16x16x32_bf16 v[124:127], v[128:131], v[170:173], v[124:127]
	v_mfma_f32_16x16x32_bf16 v[120:123], v[152:155], v[170:173], v[120:123]
	v_mfma_f32_16x16x32_bf16 v[108:111], v[128:131], v[178:181], v[108:111]
	v_mfma_f32_16x16x32_bf16 v[104:107], v[152:155], v[178:181], v[104:107]
	v_mfma_f32_16x16x32_bf16 v[92:95], v[128:131], v[190:193], v[92:95]
	v_mfma_f32_16x16x32_bf16 v[88:91], v[152:155], v[190:193], v[88:91]
	v_mfma_f32_16x16x32_bf16 v[76:79], v[128:131], v[198:201], v[76:79]
	v_mfma_f32_16x16x32_bf16 v[72:75], v[152:155], v[198:201], v[72:75]
	v_mfma_f32_16x16x32_bf16 v[124:127], v[148:151], v[174:177], v[124:127]
	v_mfma_f32_16x16x32_bf16 v[120:123], v[166:169], v[174:177], v[120:123]
	v_mfma_f32_16x16x32_bf16 v[108:111], v[148:151], v[186:189], v[108:111]
	v_mfma_f32_16x16x32_bf16 v[104:107], v[166:169], v[186:189], v[104:107]
	v_mfma_f32_16x16x32_bf16 v[92:95], v[148:151], v[194:197], v[92:95]
	v_mfma_f32_16x16x32_bf16 v[88:91], v[166:169], v[194:197], v[88:91]
	v_mfma_f32_16x16x32_bf16 v[76:79], v[148:151], v[202:205], v[76:79]
	v_mfma_f32_16x16x32_bf16 v[72:75], v[166:169], v[202:205], v[72:75]
	s_setprio 0
	s_barrier
	s_add_i32 s54, 0, 0x1c000
	s_add_i32 s55, s70, s31
	v_add_u32_e32 v165, s54, v159
	v_lshl_add_u64 v[182:183], v[182:183], 0, s[20:21]
	s_mov_b32 m0, s55
	ds_read_b128 v[206:209], v165
	ds_read_b128 v[210:213], v165 offset:1024
	ds_read_b128 v[214:217], v165 offset:2048
	ds_read_b128 v[218:221], v165 offset:3072
	global_load_lds_dwordx4 v[182:183], off
	v_lshl_add_u64 v[182:183], v[222:223], 0, s[20:21]
	s_add_i32 m0, s55, 0x2000
	s_nop 0
	global_load_lds_dwordx4 v[182:183], off
	s_barrier
	s_waitcnt lgkmcnt(0)
	s_setprio 1
	s_waitcnt lgkmcnt(0)
	v_mfma_f32_16x16x32_bf16 v[116:119], v[206:209], v[170:173], v[116:119]
	v_mfma_f32_16x16x32_bf16 v[112:115], v[214:217], v[170:173], v[112:115]
	v_mfma_f32_16x16x32_bf16 v[100:103], v[206:209], v[178:181], v[100:103]
	v_mfma_f32_16x16x32_bf16 v[96:99], v[214:217], v[178:181], v[96:99]
	v_mfma_f32_16x16x32_bf16 v[84:87], v[206:209], v[190:193], v[84:87]
	v_mfma_f32_16x16x32_bf16 v[80:83], v[214:217], v[190:193], v[80:83]
	v_mfma_f32_16x16x32_bf16 v[68:71], v[206:209], v[198:201], v[68:71]
	v_mfma_f32_16x16x32_bf16 v[64:67], v[214:217], v[198:201], v[64:67]
	v_mfma_f32_16x16x32_bf16 v[116:119], v[210:213], v[174:177], v[116:119]
	v_mfma_f32_16x16x32_bf16 v[112:115], v[218:221], v[174:177], v[112:115]
	v_mfma_f32_16x16x32_bf16 v[100:103], v[210:213], v[186:189], v[100:103]
	v_mfma_f32_16x16x32_bf16 v[96:99], v[218:221], v[186:189], v[96:99]
	v_mfma_f32_16x16x32_bf16 v[84:87], v[210:213], v[194:197], v[84:87]
	v_mfma_f32_16x16x32_bf16 v[80:83], v[218:221], v[194:197], v[80:83]
	v_mfma_f32_16x16x32_bf16 v[68:71], v[210:213], v[202:205], v[68:71]
	v_mfma_f32_16x16x32_bf16 v[64:67], v[218:221], v[202:205], v[64:67]
	s_setprio 0
	s_mov_b32 m0, s59
	v_lshl_add_u64 v[182:183], v[224:225], 0, s[20:21]
	s_barrier
	ds_read_b128 v[170:173], v162 offset:49152
	ds_read_b128 v[174:177], v162 offset:50176
	ds_read_b128 v[178:181], v162 offset:51200
	ds_read_b128 v[186:189], v162 offset:52224
	ds_read_b128 v[190:193], v162 offset:53248
	ds_read_b128 v[194:197], v162 offset:54272
	ds_read_b128 v[198:201], v162 offset:55296
	ds_read_b128 v[202:205], v162 offset:56320
	global_load_lds_dwordx4 v[182:183], off
	v_lshl_add_u64 v[182:183], v[226:227], 0, s[20:21]
	s_mov_b32 m0, s60
	s_nop 0
	global_load_lds_dwordx4 v[182:183], off
	s_barrier
; __device__ __forceinline__ unsigned cvt_pk_bf16(float lo, float hi) { const f32v2_t v = {lo, hi}; const bf16v2_t r = __builtin_convertvector(v, bf16v2_t); return __builtin_bit_cast(unsigned, r); }
; __device__ __forceinline__ float silu_f(float x) { return x * __builtin_amdgcn_rcpf(1.0f + __expf(-x)); }
; #define PG8_STAGE(bufoff, gbase, voff) do { _Pragma("unroll") for (int _i = 0; _i < 2; ++_i) \
;         __builtin_amdgcn_global_load_lds((const unsigned*)((const char*)(gbase) + (voff)[_i]), (LAS unsigned*)(lds + (bufoff) + ldsw + _i * 8192), 16, 0, 0); } while (0)
; #define PG8_WAIT_V(n) asm volatile("s_waitcnt vmcnt(" #n ")" ::: "memory")
; #define PG8_WAIT_L(n) asm volatile("s_waitcnt lgkmcnt(" #n ")" ::: "memory")
; #define PG8_BAR __builtin_amdgcn_s_barrier()
; #define PG8_SCHED __builtin_amdgcn_sched_barrier(0)
; template <class Epi>
; __device__ __forceinline__ void gemm_phase(LAS unsigned char* lds, const Gemm g, const StaticOrder& S, const Epi& E) {
;     ...
;             PG8_BAR; PG8_WAIT_L(0); PG8_MMA(1, 0, At, B0); PG8_BAR; PG8_SCHED;
;             PG8_STAGE(PG8_SB(1, 1), b3 + hstepB, voffB);
;             PG8_WAIT_V(6); PG8_BAR; PG8_MMA(1, 1, At, B1); PG8_BAR;
;         }
;         E(acc, cur, wr, wc, fr, fq);
;         if (!has_next) break;
;     __device__ __forceinline__ void operator()(const f32x4 (&acc)[2][2][4][2], const Unit& u, int wr, int wc, int fr, int fq) const {
;         const int row0 = u.pm * BM + wr * 64 + fr, col0 = (u.pn & 3) * BM + wc * 32 + 8 * fq;
;         const bool isu = u.pn < 4;
; #pragma unroll
;         for (int ai = 0; ai < 2; ++ai)
; #pragma unroll
;             for (int m = 0; m < 4; ++m) { const size_t ro = (size_t)(row0 + ai * HALF + m * 16) * DM + col0;
;                 const float rr = rsqrtf(rowss[row0 + ai * HALF + m * 16] * (1.0f / 1024.0f) + 1e-6f);
; #pragma unroll
;                 for (int bj = 0; bj < 2; ++bj) { const f32x4 v0 = acc[ai][bj][m][0] * rr, v1 = acc[ai][bj][m][1] * rr;
;                     if (isu) { u32x4 w; w.x = cvt_pk_bf16(v0[0], v0[1]); w.y = cvt_pk_bf16(v0[2], v0[3]); w.z = cvt_pk_bf16(v1[0], v1[1]); w.w = cvt_pk_bf16(v1[2], v1[3]); *(u32x4*)(U + ro + bj * HALF) = w; }
;                     else { u32x4 w; w.x = cvt_pk_bf16(silu_f(v0[0]), silu_f(v0[1])); w.y = cvt_pk_bf16(silu_f(v0[2]), silu_f(v0[3]));
	s_waitcnt lgkmcnt(0)
	s_setprio 1
	s_waitcnt lgkmcnt(0)
	v_mfma_f32_16x16x32_bf16 v[60:63], v[128:131], v[170:173], v[60:63]
	v_mfma_f32_16x16x32_bf16 v[56:59], v[152:155], v[170:173], v[56:59]
	v_mfma_f32_16x16x32_bf16 v[44:47], v[128:131], v[178:181], v[44:47]
	v_mfma_f32_16x16x32_bf16 v[40:43], v[152:155], v[178:181], v[40:43]
	v_mfma_f32_16x16x32_bf16 v[28:31], v[128:131], v[190:193], v[28:31]
	v_mfma_f32_16x16x32_bf16 v[24:27], v[152:155], v[190:193], v[24:27]
	v_mfma_f32_16x16x32_bf16 v[12:15], v[128:131], v[198:201], v[12:15]
	v_mfma_f32_16x16x32_bf16 v[8:11], v[152:155], v[198:201], v[8:11]
	v_mfma_f32_16x16x32_bf16 v[60:63], v[148:151], v[174:177], v[60:63]
	v_mfma_f32_16x16x32_bf16 v[56:59], v[166:169], v[174:177], v[56:59]
	v_mfma_f32_16x16x32_bf16 v[44:47], v[148:151], v[186:189], v[44:47]
	v_mfma_f32_16x16x32_bf16 v[40:43], v[166:169], v[186:189], v[40:43]
	v_mfma_f32_16x16x32_bf16 v[28:31], v[148:151], v[194:197], v[28:31]
	v_mfma_f32_16x16x32_bf16 v[24:27], v[166:169], v[194:197], v[24:27]
	v_mfma_f32_16x16x32_bf16 v[12:15], v[148:151], v[202:205], v[12:15]
	v_mfma_f32_16x16x32_bf16 v[8:11], v[166:169], v[202:205], v[8:11]
	s_setprio 0
	s_barrier
	s_add_u32 s52, s52, 0x40080
	s_addc_u32 s53, s53, 0
	s_add_i32 s54, s54, s31
	v_lshl_add_u64 v[128:129], s[52:53], 0, v[134:135]
	s_mov_b32 m0, s54
	s_nop 0
	global_load_lds_dwordx4 v[128:129], off
	v_lshl_add_u64 v[128:129], s[52:53], 0, v[138:139]
	s_add_i32 m0, s54, 0x2000
	s_nop 0
	global_load_lds_dwordx4 v[128:129], off
	s_waitcnt vmcnt(6)
	s_barrier
	s_setprio 1
	v_mfma_f32_16x16x32_bf16 v[52:55], v[206:209], v[170:173], v[52:55]
	v_mfma_f32_16x16x32_bf16 v[48:51], v[214:217], v[170:173], v[48:51]
	v_mfma_f32_16x16x32_bf16 v[36:39], v[206:209], v[178:181], v[36:39]
	v_mfma_f32_16x16x32_bf16 v[32:35], v[214:217], v[178:181], v[32:35]
	v_mfma_f32_16x16x32_bf16 v[20:23], v[206:209], v[190:193], v[20:23]
	v_mfma_f32_16x16x32_bf16 v[16:19], v[214:217], v[190:193], v[16:19]
	v_mfma_f32_16x16x32_bf16 v[4:7], v[206:209], v[198:201], v[4:7]
	v_mfma_f32_16x16x32_bf16 v[0:3], v[214:217], v[198:201], v[0:3]
	v_mfma_f32_16x16x32_bf16 v[52:55], v[210:213], v[174:177], v[52:55]
	v_mfma_f32_16x16x32_bf16 v[48:51], v[218:221], v[174:177], v[48:51]
	v_mfma_f32_16x16x32_bf16 v[36:39], v[210:213], v[186:189], v[36:39]
	v_mfma_f32_16x16x32_bf16 v[32:35], v[218:221], v[186:189], v[32:35]
	v_mfma_f32_16x16x32_bf16 v[20:23], v[210:213], v[194:197], v[20:23]
	v_mfma_f32_16x16x32_bf16 v[16:19], v[218:221], v[194:197], v[16:19]
	v_mfma_f32_16x16x32_bf16 v[4:7], v[210:213], v[202:205], v[4:7]
	v_mfma_f32_16x16x32_bf16 v[0:3], v[218:221], v[202:205], v[0:3]
	s_setprio 0
	s_add_i32 s69, s69, 2
	s_add_u32 s46, s46, 0x100
	s_addc_u32 s47, s47, 0
	s_add_u32 s37, s37, 0x100
	s_addc_u32 s39, s39, 0
	s_cmp_gt_u32 s69, 13
	s_barrier
	s_cbranch_scc0 .LBB0_862
	v_lshl_add_u32 v148, s6, 8, v158
	v_ashrrev_i32_e32 v149, 31, v148
	v_lshl_add_u64 v[150:151], v[148:149], 2, s[14:15]
	global_load_dword v228, v[150:151], off
	global_load_dword v229, v[150:151], off offset:64
	global_load_dword v230, v[150:151], off offset:128
	global_load_dword v231, v[150:151], off offset:192
	global_load_dword v232, v[150:151], off offset:512
	global_load_dword v233, v[150:151], off offset:576
	global_load_dword v234, v[150:151], off offset:640
	global_load_dword v235, v[150:151], off offset:704
	s_cmp_gt_i32 s8, 3
	s_cselect_b64 s[46:47], -1, 0
	s_and_b64 s[6:7], exec, s[46:47]
	s_mov_b64 s[0:1], -1
	s_waitcnt vmcnt(0)
	v_fmamk_f32 v128, v228, 0x3a800000, v164
	v_mul_f32_e32 v129, 0x4b800000, v128
	v_cmp_gt_f32_e32 vcc, s68, v128
	s_nop 1
	v_cndmask_b32_e32 v128, v128, v129, vcc
	v_rsq_f32_e32 v152, v128
	s_nop 0
	v_mul_f32_e32 v131, 0x45800000, v152
	v_cndmask_b32_e32 v152, v152, v131, vcc
	v_pk_mul_f32 v[126:127], v[126:127], v[152:153] op_sel_hi:[1,0]
	v_pk_mul_f32 v[124:125], v[124:125], v[152:153] op_sel_hi:[1,0]
	v_pk_mul_f32 v[122:123], v[122:123], v[152:153] op_sel_hi:[1,0]
	v_pk_mul_f32 v[120:121], v[120:121], v[152:153] op_sel_hi:[1,0]
	s_mov_b64 vcc, s[6:7]
	s_cbranch_vccz .LBB0_865
	v_mul_f32_e32 v128, 0xbfb8aa3b, v124
	v_mul_f32_e32 v129, 0xbfb8aa3b, v125
	v_exp_f32_e32 v128, v128
	v_exp_f32_e32 v129, v129
	v_mul_f32_e32 v130, 0xbfb8aa3b, v126
	v_exp_f32_e32 v130, v130
	v_add_f32_e32 v128, 1.0, v128
	v_add_f32_e32 v129, 1.0, v129
	v_rcp_f32_e32 v128, v128
	v_rcp_f32_e32 v129, v129
	v_mul_f32_e32 v131, 0xbfb8aa3b, v127
	v_exp_f32_e32 v131, v131
	v_mul_f32_e32 v153, 0xbfb8aa3b, v121
	v_pk_mul_f32 v[128:129], v[124:125], v[128:129]
	v_exp_f32_e32 v153, v153
	v_cvt_pk_bf16_f32 v128, v128, v129
	v_add_f32_e32 v129, 1.0, v130
	v_rcp_f32_e32 v130, v129
	v_add_f32_e32 v129, 1.0, v131
	v_rcp_f32_e32 v131, v129
	v_mul_f32_e32 v129, 0xbfb8aa3b, v120
	v_exp_f32_e32 v129, v129
	v_mul_f32_e32 v155, 0xbfb8aa3b, v123
	v_exp_f32_e32 v165, v155
	v_pk_mul_f32 v[130:131], v[126:127], v[130:131]
	v_add_f32_e32 v129, 1.0, v129
	v_rcp_f32_e32 v154, v129
	v_add_f32_e32 v129, 1.0, v153
	v_mul_f32_e32 v153, 0xbfb8aa3b, v122
	v_exp_f32_e32 v153, v153
	v_rcp_f32_e32 v155, v129
	s_mov_b64 s[0:1], 0
	v_add_f32_e32 v129, 1.0, v153
	v_rcp_f32_e32 v166, v129
	v_add_f32_e32 v129, 1.0, v165
	v_rcp_f32_e32 v167, v129
	v_cvt_pk_bf16_f32 v129, v130, v131
	v_pk_mul_f32 v[130:131], v[120:121], v[154:155]
	v_pk_mul_f32 v[154:155], v[122:123], v[166:167]
	v_cvt_pk_bf16_f32 v130, v130, v131

; __device__ __forceinline__ unsigned cvt_pk_bf16(float lo, float hi) { const f32v2_t v = {lo, hi}; const bf16v2_t r = __builtin_convertvector(v, bf16v2_t); return __builtin_bit_cast(unsigned, r); }
; __device__ __forceinline__ float silu_f(float x) { return x * __builtin_amdgcn_rcpf(1.0f + __expf(-x)); }
;     __device__ __forceinline__ void operator()(const f32x4 (&acc)[2][2][4][2], const Unit& u, int wr, int wc, int fr, int fq) const {
;     ...
;         for (int ai = 0; ai < 2; ++ai)
; #pragma unroll
;             for (int m = 0; m < 4; ++m) { const size_t ro = (size_t)(row0 + ai * HALF + m * 16) * DM + col0;
;                 const float rr = rsqrtf(rowss[row0 + ai * HALF + m * 16] * (1.0f / 1024.0f) + 1e-6f);
; #pragma unroll
;                 for (int bj = 0; bj < 2; ++bj) { const f32x4 v0 = acc[ai][bj][m][0] * rr, v1 = acc[ai][bj][m][1] * rr;
;                     if (isu) { u32x4 w; w.x = cvt_pk_bf16(v0[0], v0[1]); w.y = cvt_pk_bf16(v0[2], v0[3]); w.z = cvt_pk_bf16(v1[0], v1[1]); w.w = cvt_pk_bf16(v1[2], v1[3]); *(u32x4*)(U + ro + bj * HALF) = w; }
;                     else { u32x4 w; w.x = cvt_pk_bf16(silu_f(v0[0]), silu_f(v0[1])); w.y = cvt_pk_bf16(silu_f(v0[2]), silu_f(v0[3]));
;                            w.z = cvt_pk_bf16(silu_f(v1[0]), silu_f(v1[1])); w.w = cvt_pk_bf16(silu_f(v1[2]), silu_f(v1[3]));
;                            *(u32x4*)(SG + ro + bj * HALF) = w; } } }
.LBB0_871:
	s_add_u32 s0, s50, s0
	s_addc_u32 s1, s51, s1
	v_cvt_pk_bf16_f32 v115, v126, v127
	v_lshl_add_u64 v[116:117], v[120:121], 1, s[0:1]
	global_store_dwordx4 v[116:117], v[112:115], off offset:256
	s_and_b64 vcc, exec, s[6:7]
	s_mov_b64 s[0:1], -1
	v_or_b32_e32 v112, 16, v148
	v_ashrrev_i32_e32 v113, 31, v112
	v_lshl_add_u64 v[114:115], v[112:113], 2, s[14:15]
	v_fmamk_f32 v114, v229, 0x3a800000, v164
	v_mul_f32_e32 v115, 0x4b800000, v114
	v_cmp_gt_f32_e64 s[8:9], s68, v114
	s_nop 1
	v_cndmask_b32_e64 v114, v114, v115, s[8:9]
	v_rsq_f32_e32 v114, v114
	s_nop 0
	v_mul_f32_e32 v115, 0x45800000, v114
	v_cndmask_b32_e64 v114, v114, v115, s[8:9]
	v_pk_mul_f32 v[110:111], v[110:111], v[114:115] op_sel_hi:[1,0]
	v_pk_mul_f32 v[118:119], v[108:109], v[114:115] op_sel_hi:[1,0]
	v_pk_mul_f32 v[108:109], v[106:107], v[114:115] op_sel_hi:[1,0]
	v_pk_mul_f32 v[116:117], v[104:105], v[114:115] op_sel_hi:[1,0]
	s_cbranch_vccnz .LBB0_873
	v_mul_f32_e32 v104, 0xbfb8aa3b, v118
	v_mul_f32_e32 v105, 0xbfb8aa3b, v119
	v_exp_f32_e32 v104, v104
	v_exp_f32_e32 v105, v105
	v_mul_f32_e32 v106, 0xbfb8aa3b, v110
	v_exp_f32_e32 v106, v106
	v_add_f32_e32 v104, 1.0, v104
	v_add_f32_e32 v105, 1.0, v105
	v_rcp_f32_e32 v104, v104
	v_rcp_f32_e32 v105, v105
	v_mul_f32_e32 v107, 0xbfb8aa3b, v111
	v_exp_f32_e32 v107, v107
	v_mul_f32_e32 v115, 0xbfb8aa3b, v117
	v_pk_mul_f32 v[104:105], v[118:119], v[104:105]
	v_exp_f32_e32 v115, v115
	v_cvt_pk_bf16_f32 v104, v104, v105
	v_add_f32_e32 v105, 1.0, v106
	v_rcp_f32_e32 v106, v105
	v_add_f32_e32 v105, 1.0, v107
	v_rcp_f32_e32 v107, v105
	v_mul_f32_e32 v105, 0xbfb8aa3b, v116
	v_exp_f32_e32 v105, v105
	v_mul_f32_e32 v121, 0xbfb8aa3b, v109
	v_exp_f32_e32 v123, v121
	v_pk_mul_f32 v[106:107], v[110:111], v[106:107]
	v_add_f32_e32 v105, 1.0, v105
	v_rcp_f32_e32 v120, v105
	v_add_f32_e32 v105, 1.0, v115
	v_mul_f32_e32 v115, 0xbfb8aa3b, v108
	v_exp_f32_e32 v115, v115
	v_rcp_f32_e32 v121, v105
	s_mov_b64 s[0:1], 0
	v_add_f32_e32 v105, 1.0, v115
	v_rcp_f32_e32 v122, v105
	v_add_f32_e32 v105, 1.0, v123
	v_rcp_f32_e32 v123, v105
	v_cvt_pk_bf16_f32 v105, v106, v107
	v_pk_mul_f32 v[106:107], v[116:117], v[120:121]
	v_pk_mul_f32 v[120:121], v[108:109], v[122:123]
	v_cvt_pk_bf16_f32 v106, v106, v107

; __device__ __forceinline__ unsigned cvt_pk_bf16(float lo, float hi) { const f32v2_t v = {lo, hi}; const bf16v2_t r = __builtin_convertvector(v, bf16v2_t); return __builtin_bit_cast(unsigned, r); }
; __device__ __forceinline__ float silu_f(float x) { return x * __builtin_amdgcn_rcpf(1.0f + __expf(-x)); }
;     __device__ __forceinline__ void operator()(const f32x4 (&acc)[2][2][4][2], const Unit& u, int wr, int wc, int fr, int fq) const {
;     ...
;         for (int ai = 0; ai < 2; ++ai)
; #pragma unroll
;             for (int m = 0; m < 4; ++m) { const size_t ro = (size_t)(row0 + ai * HALF + m * 16) * DM + col0;
;                 const float rr = rsqrtf(rowss[row0 + ai * HALF + m * 16] * (1.0f / 1024.0f) + 1e-6f);
; #pragma unroll
;                 for (int bj = 0; bj < 2; ++bj) { const f32x4 v0 = acc[ai][bj][m][0] * rr, v1 = acc[ai][bj][m][1] * rr;
;                     if (isu) { u32x4 w; w.x = cvt_pk_bf16(v0[0], v0[1]); w.y = cvt_pk_bf16(v0[2], v0[3]); w.z = cvt_pk_bf16(v1[0], v1[1]); w.w = cvt_pk_bf16(v1[2], v1[3]); *(u32x4*)(U + ro + bj * HALF) = w; }
;                     else { u32x4 w; w.x = cvt_pk_bf16(silu_f(v0[0]), silu_f(v0[1])); w.y = cvt_pk_bf16(silu_f(v0[2]), silu_f(v0[3]));
;                            w.z = cvt_pk_bf16(silu_f(v1[0]), silu_f(v1[1])); w.w = cvt_pk_bf16(silu_f(v1[2]), silu_f(v1[3]));
;                            *(u32x4*)(SG + ro + bj * HALF) = w; } } }
.LBB0_879:
	s_add_u32 s0, s50, s0
	s_addc_u32 s1, s51, s1
	v_cvt_pk_bf16_f32 v99, v110, v111
	v_lshl_add_u64 v[100:101], v[108:109], 1, s[0:1]
	global_store_dwordx4 v[100:101], v[96:99], off offset:256
	s_and_b64 vcc, exec, s[6:7]
	s_mov_b64 s[0:1], -1
	v_or_b32_e32 v96, 32, v148
	v_ashrrev_i32_e32 v97, 31, v96
	v_lshl_add_u64 v[98:99], v[96:97], 2, s[14:15]
	v_fmamk_f32 v98, v230, 0x3a800000, v164
	v_mul_f32_e32 v99, 0x4b800000, v98
	v_cmp_gt_f32_e64 s[8:9], s68, v98
	s_nop 1
	v_cndmask_b32_e64 v98, v98, v99, s[8:9]
	v_rsq_f32_e32 v98, v98
	s_nop 0
	v_mul_f32_e32 v99, 0x45800000, v98
	v_cndmask_b32_e64 v98, v98, v99, s[8:9]
	v_pk_mul_f32 v[94:95], v[94:95], v[98:99] op_sel_hi:[1,0]
	v_pk_mul_f32 v[102:103], v[92:93], v[98:99] op_sel_hi:[1,0]
	v_pk_mul_f32 v[92:93], v[90:91], v[98:99] op_sel_hi:[1,0]
	v_pk_mul_f32 v[100:101], v[88:89], v[98:99] op_sel_hi:[1,0]
	s_cbranch_vccnz .LBB0_881
	v_mul_f32_e32 v88, 0xbfb8aa3b, v102
	v_mul_f32_e32 v89, 0xbfb8aa3b, v103
	v_exp_f32_e32 v88, v88
	v_exp_f32_e32 v89, v89
	v_mul_f32_e32 v90, 0xbfb8aa3b, v94
	v_exp_f32_e32 v90, v90
	v_add_f32_e32 v88, 1.0, v88
	v_add_f32_e32 v89, 1.0, v89
	v_rcp_f32_e32 v88, v88
	v_rcp_f32_e32 v89, v89
	v_mul_f32_e32 v91, 0xbfb8aa3b, v95
	v_exp_f32_e32 v91, v91
	v_mul_f32_e32 v99, 0xbfb8aa3b, v101
	v_pk_mul_f32 v[88:89], v[102:103], v[88:89]
	v_exp_f32_e32 v99, v99
	v_cvt_pk_bf16_f32 v88, v88, v89
	v_add_f32_e32 v89, 1.0, v90
	v_rcp_f32_e32 v90, v89
	v_add_f32_e32 v89, 1.0, v91
	v_rcp_f32_e32 v91, v89
	v_mul_f32_e32 v89, 0xbfb8aa3b, v100
	v_exp_f32_e32 v89, v89
	v_mul_f32_e32 v105, 0xbfb8aa3b, v93
	v_exp_f32_e32 v107, v105
	v_pk_mul_f32 v[90:91], v[94:95], v[90:91]
	v_add_f32_e32 v89, 1.0, v89
	v_rcp_f32_e32 v104, v89
	v_add_f32_e32 v89, 1.0, v99
	v_mul_f32_e32 v99, 0xbfb8aa3b, v92
	v_exp_f32_e32 v99, v99
	v_rcp_f32_e32 v105, v89
	s_mov_b64 s[0:1], 0
	v_add_f32_e32 v89, 1.0, v99
	v_rcp_f32_e32 v106, v89
	v_add_f32_e32 v89, 1.0, v107
	v_rcp_f32_e32 v107, v89
	v_cvt_pk_bf16_f32 v89, v90, v91
	v_pk_mul_f32 v[90:91], v[100:101], v[104:105]
	v_pk_mul_f32 v[104:105], v[92:93], v[106:107]
	v_cvt_pk_bf16_f32 v90, v90, v91

; __device__ __forceinline__ unsigned cvt_pk_bf16(float lo, float hi) { const f32v2_t v = {lo, hi}; const bf16v2_t r = __builtin_convertvector(v, bf16v2_t); return __builtin_bit_cast(unsigned, r); }
; __device__ __forceinline__ float silu_f(float x) { return x * __builtin_amdgcn_rcpf(1.0f + __expf(-x)); }
;     __device__ __forceinline__ void operator()(const f32x4 (&acc)[2][2][4][2], const Unit& u, int wr, int wc, int fr, int fq) const {
;     ...
;         for (int ai = 0; ai < 2; ++ai)
; #pragma unroll
;             for (int m = 0; m < 4; ++m) { const size_t ro = (size_t)(row0 + ai * HALF + m * 16) * DM + col0;
;                 const float rr = rsqrtf(rowss[row0 + ai * HALF + m * 16] * (1.0f / 1024.0f) + 1e-6f);
; #pragma unroll
;                 for (int bj = 0; bj < 2; ++bj) { const f32x4 v0 = acc[ai][bj][m][0] * rr, v1 = acc[ai][bj][m][1] * rr;
;                     if (isu) { u32x4 w; w.x = cvt_pk_bf16(v0[0], v0[1]); w.y = cvt_pk_bf16(v0[2], v0[3]); w.z = cvt_pk_bf16(v1[0], v1[1]); w.w = cvt_pk_bf16(v1[2], v1[3]); *(u32x4*)(U + ro + bj * HALF) = w; }
;                     else { u32x4 w; w.x = cvt_pk_bf16(silu_f(v0[0]), silu_f(v0[1])); w.y = cvt_pk_bf16(silu_f(v0[2]), silu_f(v0[3]));
;                            w.z = cvt_pk_bf16(silu_f(v1[0]), silu_f(v1[1])); w.w = cvt_pk_bf16(silu_f(v1[2]), silu_f(v1[3]));
;                            *(u32x4*)(SG + ro + bj * HALF) = w; } } }
.LBB0_887:
	s_add_u32 s0, s50, s0
	s_addc_u32 s1, s51, s1
	v_cvt_pk_bf16_f32 v83, v94, v95
	v_lshl_add_u64 v[84:85], v[92:93], 1, s[0:1]
	global_store_dwordx4 v[84:85], v[80:83], off offset:256
	s_and_b64 vcc, exec, s[6:7]
	s_mov_b64 s[0:1], -1
	v_or_b32_e32 v80, 48, v148
	v_ashrrev_i32_e32 v81, 31, v80
	v_lshl_add_u64 v[82:83], v[80:81], 2, s[14:15]
	v_fmamk_f32 v82, v231, 0x3a800000, v164
	v_mul_f32_e32 v83, 0x4b800000, v82
	v_cmp_gt_f32_e64 s[8:9], s68, v82
	s_nop 1
	v_cndmask_b32_e64 v82, v82, v83, s[8:9]
	v_rsq_f32_e32 v82, v82
	s_nop 0
	v_mul_f32_e32 v83, 0x45800000, v82
	v_cndmask_b32_e64 v82, v82, v83, s[8:9]
	v_pk_mul_f32 v[78:79], v[78:79], v[82:83] op_sel_hi:[1,0]
	v_pk_mul_f32 v[86:87], v[76:77], v[82:83] op_sel_hi:[1,0]
	v_pk_mul_f32 v[76:77], v[74:75], v[82:83] op_sel_hi:[1,0]
	v_pk_mul_f32 v[84:85], v[72:73], v[82:83] op_sel_hi:[1,0]
	s_cbranch_vccnz .LBB0_889
	v_mul_f32_e32 v72, 0xbfb8aa3b, v86
	v_mul_f32_e32 v73, 0xbfb8aa3b, v87
	v_exp_f32_e32 v72, v72
	v_exp_f32_e32 v73, v73
	v_mul_f32_e32 v74, 0xbfb8aa3b, v78
	v_exp_f32_e32 v74, v74
	v_add_f32_e32 v72, 1.0, v72
	v_add_f32_e32 v73, 1.0, v73
	v_rcp_f32_e32 v72, v72
	v_rcp_f32_e32 v73, v73
	v_mul_f32_e32 v75, 0xbfb8aa3b, v79
	v_exp_f32_e32 v75, v75
	v_mul_f32_e32 v83, 0xbfb8aa3b, v85
	v_pk_mul_f32 v[72:73], v[86:87], v[72:73]
	v_exp_f32_e32 v83, v83
	v_cvt_pk_bf16_f32 v72, v72, v73
	v_add_f32_e32 v73, 1.0, v74
	v_rcp_f32_e32 v74, v73
	v_add_f32_e32 v73, 1.0, v75
	v_rcp_f32_e32 v75, v73
	v_mul_f32_e32 v73, 0xbfb8aa3b, v84
	v_exp_f32_e32 v73, v73
	v_mul_f32_e32 v89, 0xbfb8aa3b, v77
	v_exp_f32_e32 v91, v89
	v_pk_mul_f32 v[74:75], v[78:79], v[74:75]
	v_add_f32_e32 v73, 1.0, v73
	v_rcp_f32_e32 v88, v73
	v_add_f32_e32 v73, 1.0, v83
	v_mul_f32_e32 v83, 0xbfb8aa3b, v76
	v_exp_f32_e32 v83, v83
	v_rcp_f32_e32 v89, v73
	s_mov_b64 s[0:1], 0
	v_add_f32_e32 v73, 1.0, v83
	v_rcp_f32_e32 v90, v73
	v_add_f32_e32 v73, 1.0, v91
	v_rcp_f32_e32 v91, v73
	v_cvt_pk_bf16_f32 v73, v74, v75
	v_pk_mul_f32 v[74:75], v[84:85], v[88:89]
	v_pk_mul_f32 v[88:89], v[76:77], v[90:91]
	v_cvt_pk_bf16_f32 v74, v74, v75

; __device__ __forceinline__ unsigned cvt_pk_bf16(float lo, float hi) { const f32v2_t v = {lo, hi}; const bf16v2_t r = __builtin_convertvector(v, bf16v2_t); return __builtin_bit_cast(unsigned, r); }
; __device__ __forceinline__ float silu_f(float x) { return x * __builtin_amdgcn_rcpf(1.0f + __expf(-x)); }
;     __device__ __forceinline__ void operator()(const f32x4 (&acc)[2][2][4][2], const Unit& u, int wr, int wc, int fr, int fq) const {
;     ...
;         for (int ai = 0; ai < 2; ++ai)
; #pragma unroll
;             for (int m = 0; m < 4; ++m) { const size_t ro = (size_t)(row0 + ai * HALF + m * 16) * DM + col0;
;                 const float rr = rsqrtf(rowss[row0 + ai * HALF + m * 16] * (1.0f / 1024.0f) + 1e-6f);
; #pragma unroll
;                 for (int bj = 0; bj < 2; ++bj) { const f32x4 v0 = acc[ai][bj][m][0] * rr, v1 = acc[ai][bj][m][1] * rr;
;                     if (isu) { u32x4 w; w.x = cvt_pk_bf16(v0[0], v0[1]); w.y = cvt_pk_bf16(v0[2], v0[3]); w.z = cvt_pk_bf16(v1[0], v1[1]); w.w = cvt_pk_bf16(v1[2], v1[3]); *(u32x4*)(U + ro + bj * HALF) = w; }
;                     else { u32x4 w; w.x = cvt_pk_bf16(silu_f(v0[0]), silu_f(v0[1])); w.y = cvt_pk_bf16(silu_f(v0[2]), silu_f(v0[3]));
;                            w.z = cvt_pk_bf16(silu_f(v1[0]), silu_f(v1[1])); w.w = cvt_pk_bf16(silu_f(v1[2]), silu_f(v1[3]));
;                            *(u32x4*)(SG + ro + bj * HALF) = w; } } }
.LBB0_895:
	s_add_u32 s0, s50, s0
	s_addc_u32 s1, s51, s1
	v_cvt_pk_bf16_f32 v67, v78, v79
	v_lshl_add_u64 v[68:69], v[76:77], 1, s[0:1]
	global_store_dwordx4 v[68:69], v[64:67], off offset:256
	s_and_b64 vcc, exec, s[6:7]
	s_mov_b64 s[0:1], -1
	v_fmamk_f32 v64, v232, 0x3a800000, v164
	v_mul_f32_e32 v65, 0x4b800000, v64
	v_cmp_gt_f32_e64 s[8:9], s68, v64
	s_nop 1
	v_cndmask_b32_e64 v64, v64, v65, s[8:9]
	v_rsq_f32_e32 v64, v64
	s_nop 0
	v_mul_f32_e32 v65, 0x45800000, v64
	v_cndmask_b32_e64 v64, v64, v65, s[8:9]
	v_pk_mul_f32 v[62:63], v[62:63], v[64:65] op_sel_hi:[1,0]
	v_pk_mul_f32 v[68:69], v[60:61], v[64:65] op_sel_hi:[1,0]
	v_pk_mul_f32 v[60:61], v[58:59], v[64:65] op_sel_hi:[1,0]
	v_pk_mul_f32 v[66:67], v[56:57], v[64:65] op_sel_hi:[1,0]
	s_cbranch_vccnz .LBB0_897
	v_mul_f32_e32 v56, 0xbfb8aa3b, v68
	v_mul_f32_e32 v57, 0xbfb8aa3b, v69
	v_exp_f32_e32 v56, v56
	v_exp_f32_e32 v57, v57
	v_mul_f32_e32 v58, 0xbfb8aa3b, v62
	v_exp_f32_e32 v58, v58
	v_add_f32_e32 v56, 1.0, v56
	v_add_f32_e32 v57, 1.0, v57
	v_rcp_f32_e32 v56, v56
	v_rcp_f32_e32 v57, v57
	v_mul_f32_e32 v59, 0xbfb8aa3b, v63
	v_exp_f32_e32 v59, v59
	v_mul_f32_e32 v65, 0xbfb8aa3b, v67
	v_pk_mul_f32 v[56:57], v[68:69], v[56:57]
	v_exp_f32_e32 v65, v65
	v_cvt_pk_bf16_f32 v56, v56, v57
	v_add_f32_e32 v57, 1.0, v58
	v_rcp_f32_e32 v58, v57
	v_add_f32_e32 v57, 1.0, v59
	v_rcp_f32_e32 v59, v57
	v_mul_f32_e32 v57, 0xbfb8aa3b, v66
	v_exp_f32_e32 v57, v57
	v_mul_f32_e32 v71, 0xbfb8aa3b, v61
	v_exp_f32_e32 v73, v71
	v_pk_mul_f32 v[58:59], v[62:63], v[58:59]
	v_add_f32_e32 v57, 1.0, v57
	v_rcp_f32_e32 v70, v57
	v_add_f32_e32 v57, 1.0, v65
	v_mul_f32_e32 v65, 0xbfb8aa3b, v60
	v_exp_f32_e32 v65, v65
	v_rcp_f32_e32 v71, v57
	s_mov_b64 s[0:1], 0
	v_add_f32_e32 v57, 1.0, v65
	v_rcp_f32_e32 v72, v57
	v_add_f32_e32 v57, 1.0, v73
	v_rcp_f32_e32 v73, v57
	v_cvt_pk_bf16_f32 v57, v58, v59
	v_pk_mul_f32 v[58:59], v[66:67], v[70:71]
	v_pk_mul_f32 v[70:71], v[60:61], v[72:73]
	v_cvt_pk_bf16_f32 v58, v58, v59

; __device__ __forceinline__ unsigned cvt_pk_bf16(float lo, float hi) { const f32v2_t v = {lo, hi}; const bf16v2_t r = __builtin_convertvector(v, bf16v2_t); return __builtin_bit_cast(unsigned, r); }
; __device__ __forceinline__ float silu_f(float x) { return x * __builtin_amdgcn_rcpf(1.0f + __expf(-x)); }
;     __device__ __forceinline__ void operator()(const f32x4 (&acc)[2][2][4][2], const Unit& u, int wr, int wc, int fr, int fq) const {
;     ...
;         for (int ai = 0; ai < 2; ++ai)
; #pragma unroll
;             for (int m = 0; m < 4; ++m) { const size_t ro = (size_t)(row0 + ai * HALF + m * 16) * DM + col0;
;                 const float rr = rsqrtf(rowss[row0 + ai * HALF + m * 16] * (1.0f / 1024.0f) + 1e-6f);
; #pragma unroll
;                 for (int bj = 0; bj < 2; ++bj) { const f32x4 v0 = acc[ai][bj][m][0] * rr, v1 = acc[ai][bj][m][1] * rr;
;                     if (isu) { u32x4 w; w.x = cvt_pk_bf16(v0[0], v0[1]); w.y = cvt_pk_bf16(v0[2], v0[3]); w.z = cvt_pk_bf16(v1[0], v1[1]); w.w = cvt_pk_bf16(v1[2], v1[3]); *(u32x4*)(U + ro + bj * HALF) = w; }
;                     else { u32x4 w; w.x = cvt_pk_bf16(silu_f(v0[0]), silu_f(v0[1])); w.y = cvt_pk_bf16(silu_f(v0[2]), silu_f(v0[3]));
;                            w.z = cvt_pk_bf16(silu_f(v1[0]), silu_f(v1[1])); w.w = cvt_pk_bf16(silu_f(v1[2]), silu_f(v1[3]));
;                            *(u32x4*)(SG + ro + bj * HALF) = w; } } }
.LBB0_903:
	s_add_u32 s0, s50, s0
	s_addc_u32 s1, s51, s1
	v_cvt_pk_bf16_f32 v51, v62, v63
	v_lshl_add_u64 v[52:53], v[60:61], 1, s[0:1]
	global_store_dwordx4 v[52:53], v[48:51], off offset:256
	s_and_b64 vcc, exec, s[6:7]
	s_mov_b64 s[0:1], -1
	v_fmamk_f32 v48, v233, 0x3a800000, v164
	v_mul_f32_e32 v49, 0x4b800000, v48
	v_cmp_gt_f32_e64 s[8:9], s68, v48
	s_nop 1
	v_cndmask_b32_e64 v48, v48, v49, s[8:9]
	v_rsq_f32_e32 v48, v48
	s_nop 0
	v_mul_f32_e32 v49, 0x45800000, v48
	v_cndmask_b32_e64 v48, v48, v49, s[8:9]
	v_pk_mul_f32 v[46:47], v[46:47], v[48:49] op_sel_hi:[1,0]
	v_pk_mul_f32 v[52:53], v[44:45], v[48:49] op_sel_hi:[1,0]
	v_pk_mul_f32 v[44:45], v[42:43], v[48:49] op_sel_hi:[1,0]
	v_pk_mul_f32 v[50:51], v[40:41], v[48:49] op_sel_hi:[1,0]
	s_cbranch_vccnz .LBB0_905
	v_mul_f32_e32 v40, 0xbfb8aa3b, v52
	v_mul_f32_e32 v41, 0xbfb8aa3b, v53
	v_exp_f32_e32 v40, v40
	v_exp_f32_e32 v41, v41
	v_mul_f32_e32 v42, 0xbfb8aa3b, v46
	v_exp_f32_e32 v42, v42
	v_add_f32_e32 v40, 1.0, v40
	v_add_f32_e32 v41, 1.0, v41
	v_rcp_f32_e32 v40, v40
	v_rcp_f32_e32 v41, v41
	v_mul_f32_e32 v43, 0xbfb8aa3b, v47
	v_exp_f32_e32 v43, v43
	v_mul_f32_e32 v49, 0xbfb8aa3b, v51
	v_pk_mul_f32 v[40:41], v[52:53], v[40:41]
	v_exp_f32_e32 v49, v49
	v_cvt_pk_bf16_f32 v40, v40, v41
	v_add_f32_e32 v41, 1.0, v42
	v_rcp_f32_e32 v42, v41
	v_add_f32_e32 v41, 1.0, v43
	v_rcp_f32_e32 v43, v41
	v_mul_f32_e32 v41, 0xbfb8aa3b, v50
	v_exp_f32_e32 v41, v41
	v_mul_f32_e32 v55, 0xbfb8aa3b, v45
	v_exp_f32_e32 v57, v55
	v_pk_mul_f32 v[42:43], v[46:47], v[42:43]
	v_add_f32_e32 v41, 1.0, v41
	v_rcp_f32_e32 v54, v41
	v_add_f32_e32 v41, 1.0, v49
	v_mul_f32_e32 v49, 0xbfb8aa3b, v44
	v_exp_f32_e32 v49, v49
	v_rcp_f32_e32 v55, v41
	s_mov_b64 s[0:1], 0
	v_add_f32_e32 v41, 1.0, v49
	v_rcp_f32_e32 v56, v41
	v_add_f32_e32 v41, 1.0, v57
	v_rcp_f32_e32 v57, v41
	v_cvt_pk_bf16_f32 v41, v42, v43
	v_pk_mul_f32 v[42:43], v[50:51], v[54:55]
	v_pk_mul_f32 v[54:55], v[44:45], v[56:57]
	v_cvt_pk_bf16_f32 v42, v42, v43

; __device__ __forceinline__ unsigned cvt_pk_bf16(float lo, float hi) { const f32v2_t v = {lo, hi}; const bf16v2_t r = __builtin_convertvector(v, bf16v2_t); return __builtin_bit_cast(unsigned, r); }
; __device__ __forceinline__ float silu_f(float x) { return x * __builtin_amdgcn_rcpf(1.0f + __expf(-x)); }
;     __device__ __forceinline__ void operator()(const f32x4 (&acc)[2][2][4][2], const Unit& u, int wr, int wc, int fr, int fq) const {
;     ...
;         for (int ai = 0; ai < 2; ++ai)
; #pragma unroll
;             for (int m = 0; m < 4; ++m) { const size_t ro = (size_t)(row0 + ai * HALF + m * 16) * DM + col0;
;                 const float rr = rsqrtf(rowss[row0 + ai * HALF + m * 16] * (1.0f / 1024.0f) + 1e-6f);
; #pragma unroll
;                 for (int bj = 0; bj < 2; ++bj) { const f32x4 v0 = acc[ai][bj][m][0] * rr, v1 = acc[ai][bj][m][1] * rr;
;                     if (isu) { u32x4 w; w.x = cvt_pk_bf16(v0[0], v0[1]); w.y = cvt_pk_bf16(v0[2], v0[3]); w.z = cvt_pk_bf16(v1[0], v1[1]); w.w = cvt_pk_bf16(v1[2], v1[3]); *(u32x4*)(U + ro + bj * HALF) = w; }
;                     else { u32x4 w; w.x = cvt_pk_bf16(silu_f(v0[0]), silu_f(v0[1])); w.y = cvt_pk_bf16(silu_f(v0[2]), silu_f(v0[3]));
;                            w.z = cvt_pk_bf16(silu_f(v1[0]), silu_f(v1[1])); w.w = cvt_pk_bf16(silu_f(v1[2]), silu_f(v1[3]));
;                            *(u32x4*)(SG + ro + bj * HALF) = w; } } }
.LBB0_911:
	s_add_u32 s0, s50, s0
	s_addc_u32 s1, s51, s1
	v_cvt_pk_bf16_f32 v35, v46, v47
	v_lshl_add_u64 v[36:37], v[44:45], 1, s[0:1]
	global_store_dwordx4 v[36:37], v[32:35], off offset:256
	s_and_b64 vcc, exec, s[6:7]
	s_mov_b64 s[0:1], -1
	v_fmamk_f32 v32, v234, 0x3a800000, v164
	v_mul_f32_e32 v33, 0x4b800000, v32
	v_cmp_gt_f32_e64 s[8:9], s68, v32
	s_nop 1
	v_cndmask_b32_e64 v32, v32, v33, s[8:9]
	v_rsq_f32_e32 v32, v32
	s_nop 0
	v_mul_f32_e32 v33, 0x45800000, v32
	v_cndmask_b32_e64 v32, v32, v33, s[8:9]
	v_pk_mul_f32 v[30:31], v[30:31], v[32:33] op_sel_hi:[1,0]
	v_pk_mul_f32 v[36:37], v[28:29], v[32:33] op_sel_hi:[1,0]
	v_pk_mul_f32 v[28:29], v[26:27], v[32:33] op_sel_hi:[1,0]
	v_pk_mul_f32 v[34:35], v[24:25], v[32:33] op_sel_hi:[1,0]
	s_cbranch_vccnz .LBB0_913
	v_mul_f32_e32 v24, 0xbfb8aa3b, v36
	v_mul_f32_e32 v25, 0xbfb8aa3b, v37
	v_exp_f32_e32 v24, v24
	v_exp_f32_e32 v25, v25
	v_mul_f32_e32 v26, 0xbfb8aa3b, v30
	v_exp_f32_e32 v26, v26
	v_add_f32_e32 v24, 1.0, v24
	v_add_f32_e32 v25, 1.0, v25
	v_rcp_f32_e32 v24, v24
	v_rcp_f32_e32 v25, v25
	v_mul_f32_e32 v27, 0xbfb8aa3b, v31
	v_exp_f32_e32 v27, v27
	v_mul_f32_e32 v33, 0xbfb8aa3b, v35
	v_pk_mul_f32 v[24:25], v[36:37], v[24:25]
	v_exp_f32_e32 v33, v33
	v_cvt_pk_bf16_f32 v24, v24, v25
	v_add_f32_e32 v25, 1.0, v26
	v_rcp_f32_e32 v26, v25
	v_add_f32_e32 v25, 1.0, v27
	v_rcp_f32_e32 v27, v25
	v_mul_f32_e32 v25, 0xbfb8aa3b, v34
	v_exp_f32_e32 v25, v25
	v_mul_f32_e32 v39, 0xbfb8aa3b, v29
	v_exp_f32_e32 v41, v39
	v_pk_mul_f32 v[26:27], v[30:31], v[26:27]
	v_add_f32_e32 v25, 1.0, v25
	v_rcp_f32_e32 v38, v25
	v_add_f32_e32 v25, 1.0, v33
	v_mul_f32_e32 v33, 0xbfb8aa3b, v28
	v_exp_f32_e32 v33, v33
	v_rcp_f32_e32 v39, v25
	s_mov_b64 s[0:1], 0
	v_add_f32_e32 v25, 1.0, v33
	v_rcp_f32_e32 v40, v25
	v_add_f32_e32 v25, 1.0, v41
	v_rcp_f32_e32 v41, v25
	v_cvt_pk_bf16_f32 v25, v26, v27
	v_pk_mul_f32 v[26:27], v[34:35], v[38:39]
	v_pk_mul_f32 v[38:39], v[28:29], v[40:41]
	v_cvt_pk_bf16_f32 v26, v26, v27

; __device__ __forceinline__ unsigned cvt_pk_bf16(float lo, float hi) { const f32v2_t v = {lo, hi}; const bf16v2_t r = __builtin_convertvector(v, bf16v2_t); return __builtin_bit_cast(unsigned, r); }
; __device__ __forceinline__ float silu_f(float x) { return x * __builtin_amdgcn_rcpf(1.0f + __expf(-x)); }
;     __device__ __forceinline__ void operator()(const f32x4 (&acc)[2][2][4][2], const Unit& u, int wr, int wc, int fr, int fq) const {
;     ...
;         for (int ai = 0; ai < 2; ++ai)
; #pragma unroll
;             for (int m = 0; m < 4; ++m) { const size_t ro = (size_t)(row0 + ai * HALF + m * 16) * DM + col0;
;                 const float rr = rsqrtf(rowss[row0 + ai * HALF + m * 16] * (1.0f / 1024.0f) + 1e-6f);
; #pragma unroll
;                 for (int bj = 0; bj < 2; ++bj) { const f32x4 v0 = acc[ai][bj][m][0] * rr, v1 = acc[ai][bj][m][1] * rr;
;                     if (isu) { u32x4 w; w.x = cvt_pk_bf16(v0[0], v0[1]); w.y = cvt_pk_bf16(v0[2], v0[3]); w.z = cvt_pk_bf16(v1[0], v1[1]); w.w = cvt_pk_bf16(v1[2], v1[3]); *(u32x4*)(U + ro + bj * HALF) = w; }
;                     else { u32x4 w; w.x = cvt_pk_bf16(silu_f(v0[0]), silu_f(v0[1])); w.y = cvt_pk_bf16(silu_f(v0[2]), silu_f(v0[3]));
;                            w.z = cvt_pk_bf16(silu_f(v1[0]), silu_f(v1[1])); w.w = cvt_pk_bf16(silu_f(v1[2]), silu_f(v1[3]));
;                            *(u32x4*)(SG + ro + bj * HALF) = w; } } }
.LBB0_919:
	s_add_u32 s0, s50, s0
	s_addc_u32 s1, s51, s1
	v_cvt_pk_bf16_f32 v19, v30, v31
	v_lshl_add_u64 v[20:21], v[28:29], 1, s[0:1]
	global_store_dwordx4 v[20:21], v[16:19], off offset:256
	s_and_b64 vcc, exec, s[6:7]
	s_mov_b64 s[0:1], -1
	v_fmamk_f32 v16, v235, 0x3a800000, v164
	v_mul_f32_e32 v17, 0x4b800000, v16
	v_cmp_gt_f32_e64 s[8:9], s68, v16
	s_nop 1
	v_cndmask_b32_e64 v16, v16, v17, s[8:9]
	v_rsq_f32_e32 v16, v16
	s_nop 0
	v_mul_f32_e32 v17, 0x45800000, v16
	v_cndmask_b32_e64 v16, v16, v17, s[8:9]
	v_pk_mul_f32 v[14:15], v[14:15], v[16:17] op_sel_hi:[1,0]
	v_pk_mul_f32 v[20:21], v[12:13], v[16:17] op_sel_hi:[1,0]
	v_pk_mul_f32 v[12:13], v[10:11], v[16:17] op_sel_hi:[1,0]
	v_pk_mul_f32 v[18:19], v[8:9], v[16:17] op_sel_hi:[1,0]
	s_cbranch_vccnz .LBB0_921
	v_mul_f32_e32 v8, 0xbfb8aa3b, v20
	v_mul_f32_e32 v9, 0xbfb8aa3b, v21
	v_exp_f32_e32 v8, v8
	v_exp_f32_e32 v9, v9
	v_mul_f32_e32 v10, 0xbfb8aa3b, v14
	v_exp_f32_e32 v10, v10
	v_add_f32_e32 v8, 1.0, v8
	v_add_f32_e32 v9, 1.0, v9
	v_rcp_f32_e32 v8, v8
	v_rcp_f32_e32 v9, v9
	v_mul_f32_e32 v11, 0xbfb8aa3b, v15
	v_exp_f32_e32 v11, v11
	v_mul_f32_e32 v17, 0xbfb8aa3b, v19
	v_pk_mul_f32 v[8:9], v[20:21], v[8:9]
	v_exp_f32_e32 v17, v17
	v_cvt_pk_bf16_f32 v8, v8, v9
	v_add_f32_e32 v9, 1.0, v10
	v_rcp_f32_e32 v10, v9
	v_add_f32_e32 v9, 1.0, v11
	v_rcp_f32_e32 v11, v9
	v_mul_f32_e32 v9, 0xbfb8aa3b, v18
	v_exp_f32_e32 v9, v9
	v_mul_f32_e32 v23, 0xbfb8aa3b, v13
	v_exp_f32_e32 v25, v23
	v_pk_mul_f32 v[10:11], v[14:15], v[10:11]
	v_add_f32_e32 v9, 1.0, v9
	v_rcp_f32_e32 v22, v9
	v_add_f32_e32 v9, 1.0, v17
	v_mul_f32_e32 v17, 0xbfb8aa3b, v12
	v_exp_f32_e32 v17, v17
	v_rcp_f32_e32 v23, v9
	s_mov_b64 s[0:1], 0
	v_add_f32_e32 v9, 1.0, v17
	v_rcp_f32_e32 v24, v9
	v_add_f32_e32 v9, 1.0, v25
	v_rcp_f32_e32 v25, v9
	v_cvt_pk_bf16_f32 v9, v10, v11
	v_pk_mul_f32 v[10:11], v[18:19], v[22:23]
	v_pk_mul_f32 v[22:23], v[12:13], v[24:25]
	v_cvt_pk_bf16_f32 v10, v10, v11
